# adds: strategy 4 - in-proj, fp8 and out K-loops: per-cluster s_setprio flips deleted, one static s_setprio 1 for waves 4-7 before the loop
# speedup vs baseline: 1.0008x; 1.0008x over previous
; __device__ __forceinline__ int lane_id_hw() { int l; asm volatile("v_mbcnt_lo_u32_b32 %0, -1, 0\n\tv_mbcnt_hi_u32_b32 %0, -1, %0" : "=v"(l)); return l; }
; #define PG8_STAGE(bufoff, gbase, voff) do { unsigned _g = (gbase); asm volatile("" : "+s"(_g));   _Pragma("unroll") for (int _i = 0; _i < 2; ++_i) \
;         __builtin_amdgcn_global_load_lds((const unsigned*)(wsb + (size_t)(unsigned)(_g + (voff)[_i])), (LAS unsigned*)(lds + (bufoff) + ldsw + _i * 8192), 16, 0, 0); } while (0)
; #define PG8_SCHED __builtin_amdgcn_sched_barrier(0)
;     ...
;         for (int t = 0; t < nt; t += 2) {
;             if constexpr (Epi::HAS_MID) { if (t == Epi::MID0 || t == Epi::MID1) { const int l2 = lane_id_hw(); E.mid(acc, cur, t == Epi::MID0 ? 0 : 1, wr, wc, l2 & 15, l2 >> 4); } }
;             const bool last = (t == nt - 2);
;             const unsigned a1 = cA + (unsigned)(t + 1) * kstep;
;             const unsigned a2 = last ? nA : cA + (unsigned)(t + 2) * kstep, b2 = last ? nB : cB + (unsigned)(t + 2) * kstep;
;             const unsigned a3 = a2 + kstep, b3 = b2 + kstep;
;             if constexpr (SP2) {
;             PG8_LDB(B0, 0, 0); PG8_LDB(B1, 0, 1); PG8_SCHED; PG8_LDA(At, 0, 0); PG8_STAGE(PG8_SA(1, 1), a1 + hstep, voffA);
;     ...
;         for (int a = 0; a < 2; ++a)
; #pragma unroll
;             for (int b = 0; b < 2; ++b)
; #pragma unroll
;                 for (int m = 0; m < 4; ++m)
; #pragma unroll
;                     for (int n = 0; n < 2; ++n) acc[a][b][m][n] = (f32x4){0.f, 0.f, 0.f, 0.f};
;         cur = nxt; cA = nA; cB = nB; ++ui;
.LBB0_278:
	s_xor_b64 s[36:37], s[4:5], -1
	s_and_b64 s[4:5], s[4:5], exec
	v_mov_b32_e32 v2, 0
	s_cselect_b32 s4, s90, s11
	s_cselect_b32 s5, s91, s10
	s_add_i32 s8, s11, 0x100080
	s_add_i32 s9, s10, 0x100
	s_mov_b32 s10, -2
	v_mov_b32_e32 v3, v2
	v_mov_b32_e32 v4, v2
	v_mov_b32_e32 v5, v2
	v_mov_b32_e32 v6, v2
	v_mov_b32_e32 v7, v2
	v_mov_b32_e32 v8, v2
	v_mov_b32_e32 v9, v2
	v_mov_b32_e32 v18, v2
	v_mov_b32_e32 v19, v2
	v_mov_b32_e32 v20, v2
	v_mov_b32_e32 v21, v2
	v_mov_b32_e32 v22, v2
	v_mov_b32_e32 v23, v2
	v_mov_b32_e32 v24, v2
	v_mov_b32_e32 v25, v2
	v_mov_b32_e32 v34, v2
	v_mov_b32_e32 v35, v2
	v_mov_b32_e32 v36, v2
	v_mov_b32_e32 v37, v2
	v_mov_b32_e32 v38, v2
	v_mov_b32_e32 v39, v2
	v_mov_b32_e32 v40, v2
	v_mov_b32_e32 v41, v2
	v_mov_b32_e32 v50, v2
	v_mov_b32_e32 v51, v2
	v_mov_b32_e32 v52, v2
	v_mov_b32_e32 v53, v2
	v_mov_b32_e32 v54, v2
	v_mov_b32_e32 v55, v2
	v_mov_b32_e32 v56, v2
	v_mov_b32_e32 v57, v2
	v_mov_b32_e32 v10, v2
	v_mov_b32_e32 v11, v2
	v_mov_b32_e32 v12, v2
	v_mov_b32_e32 v13, v2
	v_mov_b32_e32 v14, v2
	v_mov_b32_e32 v15, v2
	v_mov_b32_e32 v16, v2
	v_mov_b32_e32 v17, v2
	v_mov_b32_e32 v26, v2
	v_mov_b32_e32 v27, v2
	v_mov_b32_e32 v28, v2
	v_mov_b32_e32 v29, v2
	v_mov_b32_e32 v30, v2
	v_mov_b32_e32 v31, v2
	v_mov_b32_e32 v32, v2
	v_mov_b32_e32 v33, v2
	v_mov_b32_e32 v42, v2
	v_mov_b32_e32 v43, v2
	v_mov_b32_e32 v44, v2
	v_mov_b32_e32 v45, v2
	v_mov_b32_e32 v46, v2
	v_mov_b32_e32 v47, v2
	v_mov_b32_e32 v48, v2
	v_mov_b32_e32 v49, v2
	v_mov_b32_e32 v58, v2
	v_mov_b32_e32 v59, v2
	v_mov_b32_e32 v60, v2
	v_mov_b32_e32 v61, v2
	v_mov_b32_e32 v62, v2
	v_mov_b32_e32 v63, v2
	v_mov_b32_e32 v64, v2
	v_mov_b32_e32 v65, v2
	v_mov_b32_e32 v66, v2
	v_mov_b32_e32 v67, v2
	v_mov_b32_e32 v68, v2
	v_mov_b32_e32 v69, v2
	v_mov_b32_e32 v70, v2
	v_mov_b32_e32 v71, v2
	v_mov_b32_e32 v72, v2
	v_mov_b32_e32 v73, v2
	v_mov_b32_e32 v82, v2
	v_mov_b32_e32 v83, v2
	v_mov_b32_e32 v84, v2
	v_mov_b32_e32 v85, v2
	v_mov_b32_e32 v86, v2
	v_mov_b32_e32 v87, v2
	v_mov_b32_e32 v88, v2
	v_mov_b32_e32 v89, v2
	v_mov_b32_e32 v98, v2
	v_mov_b32_e32 v99, v2
	v_mov_b32_e32 v100, v2
	v_mov_b32_e32 v101, v2
	v_mov_b32_e32 v102, v2
	v_mov_b32_e32 v103, v2
	v_mov_b32_e32 v104, v2
	v_mov_b32_e32 v105, v2
	v_mov_b32_e32 v114, v2
	v_mov_b32_e32 v115, v2
	v_mov_b32_e32 v116, v2
	v_mov_b32_e32 v117, v2
	v_mov_b32_e32 v118, v2
	v_mov_b32_e32 v119, v2
	v_mov_b32_e32 v120, v2
	v_mov_b32_e32 v121, v2
	v_mov_b32_e32 v74, v2
	v_mov_b32_e32 v75, v2
	v_mov_b32_e32 v76, v2
	v_mov_b32_e32 v77, v2
	v_mov_b32_e32 v78, v2
	v_mov_b32_e32 v79, v2
	v_mov_b32_e32 v80, v2
	v_mov_b32_e32 v81, v2
	v_mov_b32_e32 v90, v2
	v_mov_b32_e32 v91, v2
	v_mov_b32_e32 v92, v2
	v_mov_b32_e32 v93, v2
	v_mov_b32_e32 v94, v2
	v_mov_b32_e32 v95, v2
	v_mov_b32_e32 v96, v2
	v_mov_b32_e32 v97, v2
	v_mov_b32_e32 v106, v2
	v_mov_b32_e32 v107, v2
	v_mov_b32_e32 v108, v2
	v_mov_b32_e32 v109, v2
	v_mov_b32_e32 v110, v2
	v_mov_b32_e32 v111, v2
	v_mov_b32_e32 v112, v2
	v_mov_b32_e32 v113, v2
	v_mov_b32_e32 v122, v2
	v_mov_b32_e32 v123, v2
	v_mov_b32_e32 v124, v2
	v_mov_b32_e32 v125, v2
	v_mov_b32_e32 v126, v2
	v_mov_b32_e32 v127, v2
	v_mov_b32_e32 v128, v2
	v_mov_b32_e32 v129, v2
	v_readlane_b32 s98, v255, 4
	s_nop 3
	s_cmp_lg_u32 s98, 0
	s_cbranch_scc0 .Lprio_skip_0
	s_setprio 1
.Lprio_skip_0:
.LBB0_279:
	v_readfirstlane_b32 s100, v130
	v_readfirstlane_b32 s101, v131
	s_nop 1
	s_sub_u32 s100, s100, 0x10000000
	s_subb_u32 s101, s101, 0
	s_add_i32 s11, s8, 0xfff00080
	s_cmp_eq_u32 s10, 60
	s_cselect_b32 s83, s4, s11
	s_cselect_b32 s82, s5, s9
	s_add_i32 s84, 0, 0x10000
	v_add_u32_e32 v0, s84, v152
	s_add_i32 s96, 0, 0x14000
	ds_read_b128 v[138:141], v0
	ds_read_b128 v[142:145], v0 offset:1024
	ds_read_b128 v[154:157], v0 offset:2048
	ds_read_b128 v[158:161], v0 offset:3072
	v_add_u32_e32 v0, s96, v152
	ds_read_b128 v[162:165], v0
	ds_read_b128 v[166:169], v0 offset:1024
	ds_read_b128 v[170:173], v0 offset:2048
	ds_read_b128 v[174:177], v0 offset:3072
	s_add_i32 s11, s83, 0x80
	s_mov_b32 s97, s8
	ds_read_b128 v[178:181], v153
	ds_read_b128 v[182:185], v153 offset:1024
	ds_read_b128 v[186:189], v153 offset:2048
	ds_read_b128 v[190:193], v153 offset:3072
	ds_read_b128 v[194:197], v153 offset:4096
	ds_read_b128 v[198:201], v153 offset:5120
	ds_read_b128 v[202:205], v153 offset:6144
	ds_read_b128 v[206:209], v153 offset:7168
	s_cmp_eq_i32 s10, -2
	s_cbranch_scc1 .Lin_g0_first

; #define PG8_STAGE(bufoff, gbase, voff) do { unsigned _g = (gbase); asm volatile("" : "+s"(_g));   _Pragma("unroll") for (int _i = 0; _i < 2; ++_i) \
;         __builtin_amdgcn_global_load_lds((const unsigned*)(wsb + (size_t)(unsigned)(_g + (voff)[_i])), (LAS unsigned*)(lds + (bufoff) + ldsw + _i * 8192), 16, 0, 0); } while (0)
; #define PG8_WAIT_V(n) asm volatile("s_waitcnt vmcnt(" #n ")" ::: "memory")
; #define PG8_WAIT_L(n) asm volatile("s_waitcnt lgkmcnt(" #n ")" ::: "memory")
; #define PG8_BAR __builtin_amdgcn_s_barrier()
; #define PG8_SCHED __builtin_amdgcn_sched_barrier(0)
;     ...
;             PG8_WAIT_V(8); PG8_WAIT_L(0); PG8_BAR; PG8_MMA(0, 0, At, B0); PG8_MMA(0, 1, At, B1); PG8_BAR; PG8_SCHED;
;             PG8_LDA(At, 0, 1); PG8_STAGE(PG8_SB(0, 0), b2, voffB); PG8_STAGE(PG8_SB(0, 1), b2 + hstep, voffB); PG8_STAGE(PG8_SA(0, 0), a2, voffA);
.Lin_g0_join:
	s_waitcnt lgkmcnt(0)
	s_barrier
	s_waitcnt lgkmcnt(0)
	v_mfma_f32_16x16x32_bf16 v[126:129], v[138:141], v[178:181], v[126:129]
	v_mfma_f32_16x16x32_bf16 v[122:125], v[154:157], v[178:181], v[122:125]
	v_mfma_f32_16x16x32_bf16 v[110:113], v[138:141], v[186:189], v[110:113]
	v_mfma_f32_16x16x32_bf16 v[106:109], v[154:157], v[186:189], v[106:109]
	v_mfma_f32_16x16x32_bf16 v[94:97], v[138:141], v[194:197], v[94:97]
	v_mfma_f32_16x16x32_bf16 v[90:93], v[154:157], v[194:197], v[90:93]
	v_mfma_f32_16x16x32_bf16 v[78:81], v[138:141], v[202:205], v[78:81]
	v_mfma_f32_16x16x32_bf16 v[74:77], v[154:157], v[202:205], v[74:77]
	v_mfma_f32_16x16x32_bf16 v[126:129], v[142:145], v[182:185], v[126:129]
	v_mfma_f32_16x16x32_bf16 v[122:125], v[158:161], v[182:185], v[122:125]
	v_mfma_f32_16x16x32_bf16 v[110:113], v[142:145], v[190:193], v[110:113]
	v_mfma_f32_16x16x32_bf16 v[106:109], v[158:161], v[190:193], v[106:109]
	v_mfma_f32_16x16x32_bf16 v[94:97], v[142:145], v[198:201], v[94:97]
	v_mfma_f32_16x16x32_bf16 v[90:93], v[158:161], v[198:201], v[90:93]
	v_mfma_f32_16x16x32_bf16 v[78:81], v[142:145], v[206:209], v[78:81]
	v_mfma_f32_16x16x32_bf16 v[74:77], v[158:161], v[206:209], v[74:77]
	v_mfma_f32_16x16x32_bf16 v[118:121], v[162:165], v[178:181], v[118:121]
	v_mfma_f32_16x16x32_bf16 v[114:117], v[170:173], v[178:181], v[114:117]
	v_mfma_f32_16x16x32_bf16 v[102:105], v[162:165], v[186:189], v[102:105]
	v_mfma_f32_16x16x32_bf16 v[98:101], v[170:173], v[186:189], v[98:101]
	v_mfma_f32_16x16x32_bf16 v[86:89], v[162:165], v[194:197], v[86:89]
	v_mfma_f32_16x16x32_bf16 v[82:85], v[170:173], v[194:197], v[82:85]
	v_mfma_f32_16x16x32_bf16 v[70:73], v[162:165], v[202:205], v[70:73]
	v_mfma_f32_16x16x32_bf16 v[66:69], v[170:173], v[202:205], v[66:69]
	v_mfma_f32_16x16x32_bf16 v[118:121], v[166:169], v[182:185], v[118:121]
	v_mfma_f32_16x16x32_bf16 v[114:117], v[174:177], v[182:185], v[114:117]
	v_mfma_f32_16x16x32_bf16 v[102:105], v[166:169], v[190:193], v[102:105]
	v_mfma_f32_16x16x32_bf16 v[98:101], v[174:177], v[190:193], v[98:101]
	v_mfma_f32_16x16x32_bf16 v[86:89], v[166:169], v[198:201], v[86:89]
	v_mfma_f32_16x16x32_bf16 v[82:85], v[174:177], v[198:201], v[82:85]
	v_mfma_f32_16x16x32_bf16 v[70:73], v[166:169], v[206:209], v[70:73]
	v_mfma_f32_16x16x32_bf16 v[66:69], v[174:177], v[206:209], v[66:69]
	s_barrier
	s_mov_b32 s97, s82
	ds_read_b128 v[178:181], v153 offset:16384
	ds_read_b128 v[182:185], v153 offset:17408
	ds_read_b128 v[186:189], v153 offset:18432
	ds_read_b128 v[190:193], v153 offset:19456
	ds_read_b128 v[194:197], v153 offset:20480
	ds_read_b128 v[198:201], v153 offset:21504
	ds_read_b128 v[202:205], v153 offset:22528
	ds_read_b128 v[206:209], v153 offset:23552
	s_add_i32 s84, s84, s7
	s_add_i32 vcc_lo, s97, 0x10000000
	s_add_u32 vcc_lo, s100, vcc_lo
	s_addc_u32 vcc_hi, s101, 0
	s_mov_b32 m0, s84
	s_nop 0
	global_load_lds_dwordx4 v149, vcc
	s_add_i32 m0, s84, 0x2000
	s_add_i32 s84, s82, 0x100000
	global_load_lds_dwordx4 v151, vcc
	s_add_i32 s96, s96, s7
	s_add_i32 vcc_lo, s84, 0x10000000
	s_add_u32 vcc_lo, s100, vcc_lo
	s_addc_u32 vcc_hi, s101, 0
	s_mov_b32 m0, s96
	s_nop 0
	global_load_lds_dwordx4 v149, vcc
	s_add_i32 m0, s96, 0x2000
	s_mov_b32 s84, s83
	global_load_lds_dwordx4 v151, vcc
	s_mov_b32 m0, s38
	s_add_i32 vcc_lo, s84, 0x10000000
	s_add_u32 vcc_lo, s100, vcc_lo
	s_addc_u32 vcc_hi, s101, 0
	global_load_lds_dwordx4 v148, vcc
	s_mov_b32 m0, s39
	s_nop 0
	global_load_lds_dwordx4 v150, vcc
	s_cmp_eq_i32 s10, -2
	s_cbranch_scc1 .Lin_g1_first

; #define PG8_STAGE(bufoff, gbase, voff) do { unsigned _g = (gbase); asm volatile("" : "+s"(_g));   _Pragma("unroll") for (int _i = 0; _i < 2; ++_i) \
;         __builtin_amdgcn_global_load_lds((const unsigned*)(wsb + (size_t)(unsigned)(_g + (voff)[_i])), (LAS unsigned*)(lds + (bufoff) + ldsw + _i * 8192), 16, 0, 0); } while (0)
; #define PG8_WAIT_V(n) asm volatile("s_waitcnt vmcnt(" #n ")" ::: "memory")
; #define PG8_WAIT_L(n) asm volatile("s_waitcnt lgkmcnt(" #n ")" ::: "memory")
; #define PG8_BAR __builtin_amdgcn_s_barrier()
; #define PG8_SCHED __builtin_amdgcn_sched_barrier(0)
;     ...
;             PG8_WAIT_V(8); PG8_WAIT_L(0); PG8_BAR; PG8_MMA(1, 0, At, B0); PG8_MMA(1, 1, At, B1); PG8_BAR; PG8_SCHED;
;             PG8_LDB(B0, 1, 0); PG8_LDB(B1, 1, 1); PG8_SCHED; PG8_LDA(At, 1, 0); PG8_STAGE(PG8_SA(0, 1), a2 + hstep, voffA);
.Lin_g1_join:
	s_waitcnt lgkmcnt(0)
	s_barrier
	s_waitcnt lgkmcnt(0)
	v_mfma_f32_16x16x32_bf16 v[62:65], v[138:141], v[178:181], v[62:65]
	v_mfma_f32_16x16x32_bf16 v[58:61], v[154:157], v[178:181], v[58:61]
	v_mfma_f32_16x16x32_bf16 v[46:49], v[138:141], v[186:189], v[46:49]
	v_mfma_f32_16x16x32_bf16 v[42:45], v[154:157], v[186:189], v[42:45]
	v_mfma_f32_16x16x32_bf16 v[30:33], v[138:141], v[194:197], v[30:33]
	v_mfma_f32_16x16x32_bf16 v[26:29], v[154:157], v[194:197], v[26:29]
	v_mfma_f32_16x16x32_bf16 v[14:17], v[138:141], v[202:205], v[14:17]
	v_mfma_f32_16x16x32_bf16 v[10:13], v[154:157], v[202:205], v[10:13]
	v_mfma_f32_16x16x32_bf16 v[62:65], v[142:145], v[182:185], v[62:65]
	v_mfma_f32_16x16x32_bf16 v[58:61], v[158:161], v[182:185], v[58:61]
	v_mfma_f32_16x16x32_bf16 v[46:49], v[142:145], v[190:193], v[46:49]
	v_mfma_f32_16x16x32_bf16 v[42:45], v[158:161], v[190:193], v[42:45]
	v_mfma_f32_16x16x32_bf16 v[30:33], v[142:145], v[198:201], v[30:33]
	v_mfma_f32_16x16x32_bf16 v[26:29], v[158:161], v[198:201], v[26:29]
	v_mfma_f32_16x16x32_bf16 v[14:17], v[142:145], v[206:209], v[14:17]
	v_mfma_f32_16x16x32_bf16 v[10:13], v[158:161], v[206:209], v[10:13]
	v_mfma_f32_16x16x32_bf16 v[54:57], v[162:165], v[178:181], v[54:57]
	v_mfma_f32_16x16x32_bf16 v[50:53], v[170:173], v[178:181], v[50:53]
	v_mfma_f32_16x16x32_bf16 v[38:41], v[162:165], v[186:189], v[38:41]
	v_mfma_f32_16x16x32_bf16 v[34:37], v[170:173], v[186:189], v[34:37]
	v_mfma_f32_16x16x32_bf16 v[22:25], v[162:165], v[194:197], v[22:25]
	v_mfma_f32_16x16x32_bf16 v[18:21], v[170:173], v[194:197], v[18:21]
	v_mfma_f32_16x16x32_bf16 v[6:9], v[162:165], v[202:205], v[6:9]
	v_mfma_f32_16x16x32_bf16 v[2:5], v[170:173], v[202:205], v[2:5]
	v_mfma_f32_16x16x32_bf16 v[54:57], v[166:169], v[182:185], v[54:57]
	v_mfma_f32_16x16x32_bf16 v[50:53], v[174:177], v[182:185], v[50:53]
	v_mfma_f32_16x16x32_bf16 v[38:41], v[166:169], v[190:193], v[38:41]
	v_mfma_f32_16x16x32_bf16 v[34:37], v[174:177], v[190:193], v[34:37]
	v_mfma_f32_16x16x32_bf16 v[22:25], v[166:169], v[198:201], v[22:25]
	v_mfma_f32_16x16x32_bf16 v[18:21], v[174:177], v[198:201], v[18:21]
	v_mfma_f32_16x16x32_bf16 v[6:9], v[166:169], v[206:209], v[6:9]
	v_mfma_f32_16x16x32_bf16 v[2:5], v[174:177], v[206:209], v[2:5]
	s_barrier
	s_add_i32 s84, 0, 0x18000
	v_add_u32_e32 v0, s84, v152
	s_add_i32 s96, 0, 0x1c000
	ds_read_b128 v[138:141], v0
	ds_read_b128 v[142:145], v0 offset:1024
	ds_read_b128 v[154:157], v0 offset:2048
	ds_read_b128 v[158:161], v0 offset:3072
	v_add_u32_e32 v0, s96, v152
	ds_read_b128 v[162:165], v0
	ds_read_b128 v[166:169], v0 offset:1024
	ds_read_b128 v[170:173], v0 offset:2048
	ds_read_b128 v[174:177], v0 offset:3072
	s_add_i32 s83, s83, 0x100000
	ds_read_b128 v[178:181], v153 offset:32768
	ds_read_b128 v[182:185], v153 offset:33792
	ds_read_b128 v[186:189], v153 offset:34816
	ds_read_b128 v[190:193], v153 offset:35840
	ds_read_b128 v[194:197], v153 offset:36864
	ds_read_b128 v[198:201], v153 offset:37888
	ds_read_b128 v[202:205], v153 offset:38912
	ds_read_b128 v[206:209], v153 offset:39936
	s_mov_b32 m0, s44
	s_add_i32 vcc_lo, s83, 0x10000000
	s_add_u32 vcc_lo, s100, vcc_lo
	s_addc_u32 vcc_hi, s101, 0
	global_load_lds_dwordx4 v148, vcc
	s_mov_b32 m0, s45
	s_nop 0
	global_load_lds_dwordx4 v150, vcc
	s_cmp_eq_i32 s10, -2
	s_cbranch_scc1 .Lin_g2_first

; #define PG8_STAGE(bufoff, gbase, voff) do { unsigned _g = (gbase); asm volatile("" : "+s"(_g));   _Pragma("unroll") for (int _i = 0; _i < 2; ++_i) \
;         __builtin_amdgcn_global_load_lds((const unsigned*)(wsb + (size_t)(unsigned)(_g + (voff)[_i])), (LAS unsigned*)(lds + (bufoff) + ldsw + _i * 8192), 16, 0, 0); } while (0)
; #define PG8_WAIT_V(n) asm volatile("s_waitcnt vmcnt(" #n ")" ::: "memory")
; #define PG8_WAIT_L(n) asm volatile("s_waitcnt lgkmcnt(" #n ")" ::: "memory")
; #define PG8_BAR __builtin_amdgcn_s_barrier()
; #define PG8_SCHED __builtin_amdgcn_sched_barrier(0)
;     ...
;             PG8_LDB(B0, 1, 0); PG8_LDB(B1, 1, 1); PG8_SCHED; PG8_LDA(At, 1, 0); PG8_STAGE(PG8_SA(0, 1), a2 + hstep, voffA);
;             PG8_WAIT_V(8); PG8_WAIT_L(0); PG8_BAR; PG8_MMA(0, 0, At, B0); PG8_MMA(0, 1, At, B1); PG8_BAR; PG8_SCHED;
;             PG8_LDA(At, 1, 1); PG8_STAGE(PG8_SB(1, 0), b3, voffB); PG8_STAGE(PG8_SB(1, 1), b3 + hstep, voffB); PG8_STAGE(PG8_SA(1, 0), a3, voffA);
;             PG8_WAIT_V(8); PG8_WAIT_L(0); PG8_BAR; PG8_MMA(1, 0, At, B0); PG8_MMA(1, 1, At, B1); PG8_BAR; PG8_SCHED;
;     __device__ __forceinline__ void operator()(const f32x4 (&acc)[2][2][4][2], const pg8::GUnit& u, int wr, int wc, int fr, int fq) const {
;         bf16_t* base; int ldc, mode = 0, bjs = 128; int rowb = u.pm * 256 + wr * 64 + fr, colb = u.pn * 256 + wc * 32 + 8 * fq;
;         if (u.kind == 0) { base = P; ldc = INW; const int pn = u.pn; if (pn >= GA / 256) mode = 1; else if ((pn >= ZA / 256 && pn < QB / 256) || (pn >= ZB / 256 && pn < QM / 256) || (pn >= ZM / 256)) mode = 2;
;             if (GATES_FP8) {
;                 int nh = 0, hp = 0; size_t off = 0;
;                 if (pn >= KA / 256 && pn < VA / 256) { nh = 12; hp = pn - KA / 256; off = WS_KNA; } else if (pn >= VA / 256 && pn < ZA / 256) { nh = 12; hp = pn - VA / 256; off = WS_VNA; }
;                 else if (pn >= KB / 256 && pn < VB / 256) { nh = 4; hp = pn - KB / 256; off = WS_KSW; } else if (pn >= VB / 256 && pn < ZB / 256) { nh = 4; hp = pn - VB / 256; off = WS_VSW; }
;                 if (nh) { const int b = u.pm >> 3; base = wsb16 + off / 2; ldc = 128; bjs = SEQ * 128; rowb = (b * nh + 2 * hp) * SEQ + (u.pm & 7) * 256 + wr * 64 + fr; colb = wc * 32 + 8 * fq; } } }
;         else { base = (u.kind == 1) ? KVM0 : KVM1; ldc = KVW; }
.Lin_g2_join:
	s_waitcnt lgkmcnt(0)
	s_barrier
	s_waitcnt lgkmcnt(0)
	v_mfma_f32_16x16x32_bf16 v[126:129], v[138:141], v[178:181], v[126:129]
	v_mfma_f32_16x16x32_bf16 v[122:125], v[154:157], v[178:181], v[122:125]
	v_mfma_f32_16x16x32_bf16 v[110:113], v[138:141], v[186:189], v[110:113]
	v_mfma_f32_16x16x32_bf16 v[106:109], v[154:157], v[186:189], v[106:109]
	v_mfma_f32_16x16x32_bf16 v[94:97], v[138:141], v[194:197], v[94:97]
	v_mfma_f32_16x16x32_bf16 v[90:93], v[154:157], v[194:197], v[90:93]
	v_mfma_f32_16x16x32_bf16 v[78:81], v[138:141], v[202:205], v[78:81]
	v_mfma_f32_16x16x32_bf16 v[74:77], v[154:157], v[202:205], v[74:77]
	v_mfma_f32_16x16x32_bf16 v[126:129], v[142:145], v[182:185], v[126:129]
	v_mfma_f32_16x16x32_bf16 v[122:125], v[158:161], v[182:185], v[122:125]
	v_mfma_f32_16x16x32_bf16 v[110:113], v[142:145], v[190:193], v[110:113]
	v_mfma_f32_16x16x32_bf16 v[106:109], v[158:161], v[190:193], v[106:109]
	v_mfma_f32_16x16x32_bf16 v[94:97], v[142:145], v[198:201], v[94:97]
	v_mfma_f32_16x16x32_bf16 v[90:93], v[158:161], v[198:201], v[90:93]
	v_mfma_f32_16x16x32_bf16 v[78:81], v[142:145], v[206:209], v[78:81]
	v_mfma_f32_16x16x32_bf16 v[74:77], v[158:161], v[206:209], v[74:77]
	v_mfma_f32_16x16x32_bf16 v[118:121], v[162:165], v[178:181], v[118:121]
	v_mfma_f32_16x16x32_bf16 v[114:117], v[170:173], v[178:181], v[114:117]
	v_mfma_f32_16x16x32_bf16 v[102:105], v[162:165], v[186:189], v[102:105]
	v_mfma_f32_16x16x32_bf16 v[98:101], v[170:173], v[186:189], v[98:101]
	v_mfma_f32_16x16x32_bf16 v[86:89], v[162:165], v[194:197], v[86:89]
	v_mfma_f32_16x16x32_bf16 v[82:85], v[170:173], v[194:197], v[82:85]
	v_mfma_f32_16x16x32_bf16 v[70:73], v[162:165], v[202:205], v[70:73]
	v_mfma_f32_16x16x32_bf16 v[66:69], v[170:173], v[202:205], v[66:69]
	v_mfma_f32_16x16x32_bf16 v[118:121], v[166:169], v[182:185], v[118:121]
	v_mfma_f32_16x16x32_bf16 v[114:117], v[174:177], v[182:185], v[114:117]
	v_mfma_f32_16x16x32_bf16 v[102:105], v[166:169], v[190:193], v[102:105]
	v_mfma_f32_16x16x32_bf16 v[98:101], v[174:177], v[190:193], v[98:101]
	v_mfma_f32_16x16x32_bf16 v[86:89], v[166:169], v[198:201], v[86:89]
	v_mfma_f32_16x16x32_bf16 v[82:85], v[174:177], v[198:201], v[82:85]
	v_mfma_f32_16x16x32_bf16 v[70:73], v[166:169], v[206:209], v[70:73]
	v_mfma_f32_16x16x32_bf16 v[66:69], v[174:177], v[206:209], v[66:69]
	s_barrier
	s_add_i32 s83, s82, 0x80
	ds_read_b128 v[178:181], v153 offset:49152
	ds_read_b128 v[182:185], v153 offset:50176
	ds_read_b128 v[186:189], v153 offset:51200
	ds_read_b128 v[190:193], v153 offset:52224
	ds_read_b128 v[194:197], v153 offset:53248
	ds_read_b128 v[198:201], v153 offset:54272
	ds_read_b128 v[202:205], v153 offset:55296
	ds_read_b128 v[206:209], v153 offset:56320
	s_add_i32 s84, s84, s7
	s_add_i32 vcc_lo, s83, 0x10000000
	s_add_u32 vcc_lo, s100, vcc_lo
	s_addc_u32 vcc_hi, s101, 0
	s_mov_b32 m0, s84
	s_nop 0
	global_load_lds_dwordx4 v149, vcc
	s_add_i32 m0, s84, 0x2000
	s_add_i32 s82, s82, 0x100080
	global_load_lds_dwordx4 v151, vcc
	s_add_i32 s83, s96, s7
	s_add_i32 vcc_lo, s82, 0x10000000
	s_add_u32 vcc_lo, s100, vcc_lo
	s_addc_u32 vcc_hi, s101, 0
	s_mov_b32 m0, s83
	s_nop 0
	global_load_lds_dwordx4 v149, vcc
	s_add_i32 m0, s83, 0x2000
	s_nop 0
	global_load_lds_dwordx4 v151, vcc
	s_mov_b32 m0, s46
	s_add_i32 vcc_lo, s11, 0x10000000
	s_add_u32 vcc_lo, s100, vcc_lo
	s_addc_u32 vcc_hi, s101, 0
	global_load_lds_dwordx4 v148, vcc
	s_mov_b32 m0, s47
	s_nop 0
	global_load_lds_dwordx4 v150, vcc
	s_waitcnt vmcnt(8)
	s_waitcnt lgkmcnt(0)
	s_barrier
	s_waitcnt lgkmcnt(0)
	v_mfma_f32_16x16x32_bf16 v[62:65], v[138:141], v[178:181], v[62:65]
	v_mfma_f32_16x16x32_bf16 v[58:61], v[154:157], v[178:181], v[58:61]
	v_mfma_f32_16x16x32_bf16 v[46:49], v[138:141], v[186:189], v[46:49]
	v_mfma_f32_16x16x32_bf16 v[42:45], v[154:157], v[186:189], v[42:45]
	v_mfma_f32_16x16x32_bf16 v[30:33], v[138:141], v[194:197], v[30:33]
	v_mfma_f32_16x16x32_bf16 v[26:29], v[154:157], v[194:197], v[26:29]
	v_mfma_f32_16x16x32_bf16 v[14:17], v[138:141], v[202:205], v[14:17]
	v_mfma_f32_16x16x32_bf16 v[10:13], v[154:157], v[202:205], v[10:13]
	v_mfma_f32_16x16x32_bf16 v[62:65], v[142:145], v[182:185], v[62:65]
	v_mfma_f32_16x16x32_bf16 v[58:61], v[158:161], v[182:185], v[58:61]
	v_mfma_f32_16x16x32_bf16 v[46:49], v[142:145], v[190:193], v[46:49]
	v_mfma_f32_16x16x32_bf16 v[42:45], v[158:161], v[190:193], v[42:45]
	v_mfma_f32_16x16x32_bf16 v[30:33], v[142:145], v[198:201], v[30:33]
	v_mfma_f32_16x16x32_bf16 v[26:29], v[158:161], v[198:201], v[26:29]
	v_mfma_f32_16x16x32_bf16 v[14:17], v[142:145], v[206:209], v[14:17]
	v_mfma_f32_16x16x32_bf16 v[10:13], v[158:161], v[206:209], v[10:13]
	v_mfma_f32_16x16x32_bf16 v[54:57], v[162:165], v[178:181], v[54:57]
	v_mfma_f32_16x16x32_bf16 v[50:53], v[170:173], v[178:181], v[50:53]
	v_mfma_f32_16x16x32_bf16 v[38:41], v[162:165], v[186:189], v[38:41]
	v_mfma_f32_16x16x32_bf16 v[34:37], v[170:173], v[186:189], v[34:37]
	v_mfma_f32_16x16x32_bf16 v[22:25], v[162:165], v[194:197], v[22:25]
	v_mfma_f32_16x16x32_bf16 v[18:21], v[170:173], v[194:197], v[18:21]
	v_mfma_f32_16x16x32_bf16 v[6:9], v[162:165], v[202:205], v[6:9]
	v_mfma_f32_16x16x32_bf16 v[2:5], v[170:173], v[202:205], v[2:5]
	v_mfma_f32_16x16x32_bf16 v[54:57], v[166:169], v[182:185], v[54:57]
	v_mfma_f32_16x16x32_bf16 v[50:53], v[174:177], v[182:185], v[50:53]
	v_mfma_f32_16x16x32_bf16 v[38:41], v[166:169], v[190:193], v[38:41]
	v_mfma_f32_16x16x32_bf16 v[34:37], v[174:177], v[190:193], v[34:37]
	v_mfma_f32_16x16x32_bf16 v[22:25], v[166:169], v[198:201], v[22:25]
	v_mfma_f32_16x16x32_bf16 v[18:21], v[174:177], v[198:201], v[18:21]
	v_mfma_f32_16x16x32_bf16 v[6:9], v[166:169], v[206:209], v[6:9]
	v_mfma_f32_16x16x32_bf16 v[2:5], v[174:177], v[206:209], v[2:5]
	s_barrier
	s_add_i32 s10, s10, 2
	s_addk_i32 s8, 0x100
	s_addk_i32 s9, 0x100
	s_cmp_gt_u32 s10, 61
	s_cbranch_scc0 .LBB0_279
	s_setprio 0
	s_mov_b64 s[10:11], -1
	s_mov_b64 s[4:5], 0
	s_cmp_lt_i32 s18, 1
	s_mov_b64 s[8:9], 0
	v_mbcnt_lo_u32_b32 v0, -1, 0
	v_mbcnt_hi_u32_b32 v0, -1, v0
	s_cbranch_scc1 .LBB0_295
	s_cmp_lg_u32 s18, 1
	s_cselect_b64 s[8:9], -1, 0
	s_cbranch_execz .LBB0_296

; __device__ __forceinline__ int lane_id_hw() { int l; asm volatile("v_mbcnt_lo_u32_b32 %0, -1, 0\n\tv_mbcnt_hi_u32_b32 %0, -1, %0" : "=v"(l)); return l; }
; #define PG8_STAGE(bufoff, gbase, voff) do { unsigned _g = (gbase); asm volatile("" : "+s"(_g));   _Pragma("unroll") for (int _i = 0; _i < 2; ++_i) \
;         __builtin_amdgcn_global_load_lds((const unsigned*)(wsb + (size_t)(unsigned)(_g + (voff)[_i])), (LAS unsigned*)(lds + (bufoff) + ldsw + _i * 8192), 16, 0, 0); } while (0)
; #define PG8_WAIT_V(n) asm volatile("s_waitcnt vmcnt(" #n ")" ::: "memory")
; #define PG8_WAIT_L(n) asm volatile("s_waitcnt lgkmcnt(" #n ")" ::: "memory")
; #define PG8_BAR __builtin_amdgcn_s_barrier()
; #define PG8_SCHED __builtin_amdgcn_sched_barrier(0)
;     ...
;         for (int t = 0; t < nt; t += 2) {
;             if constexpr (Epi::HAS_MID) { if (t == Epi::MID0 || t == Epi::MID1) { const int l2 = lane_id_hw(); E.mid(acc, cur, t == Epi::MID0 ? 0 : 1, wr, wc, l2 & 15, l2 >> 4); } }
;             const bool last = (t == nt - 2);
;             const unsigned a1 = cA + (unsigned)(t + 1) * kstep;
;             const unsigned a2 = last ? nA : cA + (unsigned)(t + 2) * kstep, b2 = last ? nB : cB + (unsigned)(t + 2) * kstep;
;             const unsigned a3 = a2 + kstep, b3 = b2 + kstep;
;             if constexpr (SP2) {
;             PG8_LDB(B0, 0, 0); PG8_LDB(B1, 0, 1); PG8_SCHED; PG8_LDA(At, 0, 0); PG8_STAGE(PG8_SA(1, 1), a1 + hstep, voffA);
;             PG8_WAIT_V(8); PG8_WAIT_L(0); PG8_BAR; PG8_MMA(0, 0, At, B0); PG8_MMA(0, 1, At, B1); PG8_BAR; PG8_SCHED;
;     ...
;         for (int a = 0; a < 2; ++a)
; #pragma unroll
;             for (int b = 0; b < 2; ++b)
; #pragma unroll
;                 for (int m = 0; m < 4; ++m)
; #pragma unroll
;                     for (int n = 0; n < 2; ++n) acc[a][b][m][n] = (f32x4){0.f, 0.f, 0.f, 0.f};
;         cur = nxt; cA = nA; cB = nB; ++ui;
.LBB0_558:
	v_mov_b32_e32 v2, 0
	s_add_i32 s44, s44, 0x80080
	s_addk_i32 s45, 0x100
	s_mov_b32 s46, -2
	v_mov_b32_e32 v3, v2
	v_mov_b32_e32 v4, v2
	v_mov_b32_e32 v5, v2
	v_mov_b32_e32 v6, v2
	v_mov_b32_e32 v7, v2
	v_mov_b32_e32 v8, v2
	v_mov_b32_e32 v9, v2
	v_mov_b32_e32 v18, v2
	v_mov_b32_e32 v19, v2
	v_mov_b32_e32 v20, v2
	v_mov_b32_e32 v21, v2
	v_mov_b32_e32 v22, v2
	v_mov_b32_e32 v23, v2
	v_mov_b32_e32 v24, v2
	v_mov_b32_e32 v25, v2
	v_mov_b32_e32 v34, v2
	v_mov_b32_e32 v35, v2
	v_mov_b32_e32 v36, v2
	v_mov_b32_e32 v37, v2
	v_mov_b32_e32 v38, v2
	v_mov_b32_e32 v39, v2
	v_mov_b32_e32 v40, v2
	v_mov_b32_e32 v41, v2
	v_mov_b32_e32 v50, v2
	v_mov_b32_e32 v51, v2
	v_mov_b32_e32 v52, v2
	v_mov_b32_e32 v53, v2
	v_mov_b32_e32 v54, v2
	v_mov_b32_e32 v55, v2
	v_mov_b32_e32 v56, v2
	v_mov_b32_e32 v57, v2
	v_mov_b32_e32 v10, v2
	v_mov_b32_e32 v11, v2
	v_mov_b32_e32 v12, v2
	v_mov_b32_e32 v13, v2
	v_mov_b32_e32 v14, v2
	v_mov_b32_e32 v15, v2
	v_mov_b32_e32 v16, v2
	v_mov_b32_e32 v17, v2
	v_mov_b32_e32 v26, v2
	v_mov_b32_e32 v27, v2
	v_mov_b32_e32 v28, v2
	v_mov_b32_e32 v29, v2
	v_mov_b32_e32 v30, v2
	v_mov_b32_e32 v31, v2
	v_mov_b32_e32 v32, v2
	v_mov_b32_e32 v33, v2
	v_mov_b32_e32 v42, v2
	v_mov_b32_e32 v43, v2
	v_mov_b32_e32 v44, v2
	v_mov_b32_e32 v45, v2
	v_mov_b32_e32 v46, v2
	v_mov_b32_e32 v47, v2
	v_mov_b32_e32 v48, v2
	v_mov_b32_e32 v49, v2
	v_mov_b32_e32 v58, v2
	v_mov_b32_e32 v59, v2
	v_mov_b32_e32 v60, v2
	v_mov_b32_e32 v61, v2
	v_mov_b32_e32 v62, v2
	v_mov_b32_e32 v63, v2
	v_mov_b32_e32 v64, v2
	v_mov_b32_e32 v65, v2
	v_mov_b32_e32 v66, v2
	v_mov_b32_e32 v67, v2
	v_mov_b32_e32 v68, v2
	v_mov_b32_e32 v69, v2
	v_mov_b32_e32 v70, v2
	v_mov_b32_e32 v71, v2
	v_mov_b32_e32 v72, v2
	v_mov_b32_e32 v73, v2
	v_mov_b32_e32 v82, v2
	v_mov_b32_e32 v83, v2
	v_mov_b32_e32 v84, v2
	v_mov_b32_e32 v85, v2
	v_mov_b32_e32 v86, v2
	v_mov_b32_e32 v87, v2
	v_mov_b32_e32 v88, v2
	v_mov_b32_e32 v89, v2
	v_mov_b32_e32 v98, v2
	v_mov_b32_e32 v99, v2
	v_mov_b32_e32 v100, v2
	v_mov_b32_e32 v101, v2
	v_mov_b32_e32 v102, v2
	v_mov_b32_e32 v103, v2
	v_mov_b32_e32 v104, v2
	v_mov_b32_e32 v105, v2
	v_mov_b32_e32 v114, v2
	v_mov_b32_e32 v115, v2
	v_mov_b32_e32 v116, v2
	v_mov_b32_e32 v117, v2
	v_mov_b32_e32 v118, v2
	v_mov_b32_e32 v119, v2
	v_mov_b32_e32 v120, v2
	v_mov_b32_e32 v121, v2
	v_mov_b32_e32 v74, v2
	v_mov_b32_e32 v75, v2
	v_mov_b32_e32 v76, v2
	v_mov_b32_e32 v77, v2
	v_mov_b32_e32 v78, v2
	v_mov_b32_e32 v79, v2
	v_mov_b32_e32 v80, v2
	v_mov_b32_e32 v81, v2
	v_mov_b32_e32 v90, v2
	v_mov_b32_e32 v91, v2
	v_mov_b32_e32 v92, v2
	v_mov_b32_e32 v93, v2
	v_mov_b32_e32 v94, v2
	v_mov_b32_e32 v95, v2
	v_mov_b32_e32 v96, v2
	v_mov_b32_e32 v97, v2
	v_mov_b32_e32 v106, v2
	v_mov_b32_e32 v107, v2
	v_mov_b32_e32 v108, v2
	v_mov_b32_e32 v109, v2
	v_mov_b32_e32 v110, v2
	v_mov_b32_e32 v111, v2
	v_mov_b32_e32 v112, v2
	v_mov_b32_e32 v113, v2
	v_mov_b32_e32 v122, v2
	v_mov_b32_e32 v123, v2
	v_mov_b32_e32 v124, v2
	v_mov_b32_e32 v125, v2
	v_mov_b32_e32 v126, v2
	v_mov_b32_e32 v127, v2
	v_mov_b32_e32 v128, v2
	v_mov_b32_e32 v129, v2
	v_readlane_b32 s98, v255, 4
	s_nop 3
	s_cmp_lg_u32 s98, 0
	s_cbranch_scc0 .Lprio_skip_1
	s_setprio 1
.Lprio_skip_1:
.LBB0_559:
	v_readfirstlane_b32 s100, v130
	v_readfirstlane_b32 s101, v131
	s_nop 1
	s_sub_u32 s100, s100, 0x10000000
	s_subb_u32 s101, s101, 0
	s_add_i32 s47, s44, 0xfff80080
	s_cmp_eq_u32 s46, 28
	s_cselect_b32 s83, s36, s47
	s_cselect_b32 s47, s37, s45
	s_add_i32 s84, 0, 0x10000
	v_add_u32_e32 v0, s84, v138
	s_add_i32 s86, 0, 0x14000
	ds_read_b128 v[140:143], v0
	ds_read_b128 v[144:147], v0 offset:1024
	ds_read_b128 v[148:151], v0 offset:2048
	ds_read_b128 v[152:155], v0 offset:3072
	v_add_u32_e32 v0, s86, v138
	ds_read_b128 v[156:159], v0
	ds_read_b128 v[160:163], v0 offset:1024
	ds_read_b128 v[164:167], v0 offset:2048
	ds_read_b128 v[168:171], v0 offset:3072
	s_add_i32 s82, s83, 0x80
	s_mov_b32 s87, s44
	ds_read_b128 v[172:175], v139
	ds_read_b128 v[176:179], v139 offset:1024
	ds_read_b128 v[180:183], v139 offset:2048
	ds_read_b128 v[184:187], v139 offset:3072
	ds_read_b128 v[188:191], v139 offset:4096
	ds_read_b128 v[192:195], v139 offset:5120
	ds_read_b128 v[196:199], v139 offset:6144
	ds_read_b128 v[200:203], v139 offset:7168
	s_add_i32 m0, s9, 0xc000
	s_add_i32 vcc_lo, s87, 0x10000000
	s_add_u32 vcc_lo, s100, vcc_lo
	s_addc_u32 vcc_hi, s101, 0
	global_load_lds_dwordx4 v134, vcc
	s_add_i32 m0, s9, 0xe000
	s_nop 0
	global_load_lds_dwordx4 v136, vcc
	s_waitcnt vmcnt(8)
	s_waitcnt lgkmcnt(0)
	s_barrier
	s_waitcnt lgkmcnt(0)
	v_mfma_f32_16x16x128_f8f6f4 v[126:129], v[140:147], v[172:179], v[126:129]
	v_mfma_f32_16x16x128_f8f6f4 v[122:125], v[148:155], v[172:179], v[122:125]
	v_mfma_f32_16x16x128_f8f6f4 v[110:113], v[140:147], v[180:187], v[110:113]
	v_mfma_f32_16x16x128_f8f6f4 v[106:109], v[148:155], v[180:187], v[106:109]
	v_mfma_f32_16x16x128_f8f6f4 v[204:207], v[140:147], v[188:195], v[94:97]
	v_mfma_f32_16x16x128_f8f6f4 v[208:211], v[148:155], v[188:195], v[90:93]
	v_mfma_f32_16x16x128_f8f6f4 v[212:215], v[140:147], v[196:203], v[78:81]
	v_mfma_f32_16x16x128_f8f6f4 v[216:219], v[148:155], v[196:203], v[74:77]
	v_mfma_f32_16x16x128_f8f6f4 v[118:121], v[156:163], v[172:179], v[118:121]
	v_mfma_f32_16x16x128_f8f6f4 v[114:117], v[164:171], v[172:179], v[114:117]
	v_mfma_f32_16x16x128_f8f6f4 v[102:105], v[156:163], v[180:187], v[102:105]
	v_mfma_f32_16x16x128_f8f6f4 v[98:101], v[164:171], v[180:187], v[98:101]
	v_mfma_f32_16x16x128_f8f6f4 v[172:175], v[156:163], v[188:195], v[86:89]
	v_mfma_f32_16x16x128_f8f6f4 v[176:179], v[164:171], v[188:195], v[82:85]
	v_mfma_f32_16x16x128_f8f6f4 v[180:183], v[156:163], v[196:203], v[70:73]
	v_mfma_f32_16x16x128_f8f6f4 v[184:187], v[164:171], v[196:203], v[66:69]
	s_barrier
; #define PG8_STAGE(bufoff, gbase, voff) do { unsigned _g = (gbase); asm volatile("" : "+s"(_g));   _Pragma("unroll") for (int _i = 0; _i < 2; ++_i) \
;         __builtin_amdgcn_global_load_lds((const unsigned*)(wsb + (size_t)(unsigned)(_g + (voff)[_i])), (LAS unsigned*)(lds + (bufoff) + ldsw + _i * 8192), 16, 0, 0); } while (0)
; #define PG8_WAIT_V(n) asm volatile("s_waitcnt vmcnt(" #n ")" ::: "memory")
; #define PG8_WAIT_L(n) asm volatile("s_waitcnt lgkmcnt(" #n ")" ::: "memory")
; #define PG8_BAR __builtin_amdgcn_s_barrier()
; #define PG8_SCHED __builtin_amdgcn_sched_barrier(0)
;     ...
;             PG8_LDA(At, 0, 1); PG8_STAGE(PG8_SB(0, 0), b2, voffB); PG8_STAGE(PG8_SB(0, 1), b2 + hstep, voffB); PG8_STAGE(PG8_SA(0, 0), a2, voffA);
;             PG8_WAIT_V(8); PG8_WAIT_L(0); PG8_BAR; PG8_MMA(1, 0, At, B0); PG8_MMA(1, 1, At, B1); PG8_BAR; PG8_SCHED;
;             PG8_LDB(B0, 1, 0); PG8_LDB(B1, 1, 1); PG8_SCHED; PG8_LDA(At, 1, 0); PG8_STAGE(PG8_SA(0, 1), a2 + hstep, voffA);
;             PG8_WAIT_V(8); PG8_WAIT_L(0); PG8_BAR; PG8_MMA(0, 0, At, B0); PG8_MMA(0, 1, At, B1); PG8_BAR; PG8_SCHED;
	s_mov_b32 s87, s47
	s_nop 3
	ds_read_b128 v[66:69], v139 offset:16384
	ds_read_b128 v[70:73], v139 offset:17408
	ds_read_b128 v[74:77], v139 offset:18432
	ds_read_b128 v[78:81], v139 offset:19456
	ds_read_b128 v[82:85], v139 offset:20480
	ds_read_b128 v[86:89], v139 offset:21504
	ds_read_b128 v[90:93], v139 offset:22528
	ds_read_b128 v[94:97], v139 offset:23552
	s_add_i32 s84, s84, s7
	s_add_i32 vcc_lo, s87, 0x10000000
	s_add_u32 vcc_lo, s100, vcc_lo
	s_addc_u32 vcc_hi, s101, 0
	s_mov_b32 m0, s84
	s_nop 0
	global_load_lds_dwordx4 v135, vcc
	s_add_i32 m0, s84, 0x2000
	s_add_i32 s84, s47, 0x80000
	global_load_lds_dwordx4 v137, vcc
	s_add_i32 s86, s86, s7
	s_add_i32 vcc_lo, s84, 0x10000000
	s_add_u32 vcc_lo, s100, vcc_lo
	s_addc_u32 vcc_hi, s101, 0
	s_mov_b32 m0, s86
	s_nop 0
	global_load_lds_dwordx4 v135, vcc
	s_add_i32 m0, s86, 0x2000
	s_mov_b32 s84, s83
	global_load_lds_dwordx4 v137, vcc
	s_mov_b32 m0, s9
	s_add_i32 vcc_lo, s84, 0x10000000
	s_add_u32 vcc_lo, s100, vcc_lo
	s_addc_u32 vcc_hi, s101, 0
	global_load_lds_dwordx4 v134, vcc
	s_mov_b32 m0, s11
	s_nop 0
	global_load_lds_dwordx4 v136, vcc
	s_waitcnt vmcnt(8)
	s_waitcnt lgkmcnt(0)
	s_barrier
	s_waitcnt lgkmcnt(0)
	v_mfma_f32_16x16x128_f8f6f4 v[62:65], v[140:147], v[66:73], v[62:65]
	v_mfma_f32_16x16x128_f8f6f4 v[58:61], v[148:155], v[66:73], v[58:61]
	v_mfma_f32_16x16x128_f8f6f4 v[188:191], v[140:147], v[74:81], v[46:49]
	v_mfma_f32_16x16x128_f8f6f4 v[192:195], v[148:155], v[74:81], v[42:45]
	v_mfma_f32_16x16x128_f8f6f4 v[196:199], v[140:147], v[82:89], v[30:33]
	v_mfma_f32_16x16x128_f8f6f4 v[200:203], v[148:155], v[82:89], v[26:29]
	v_mfma_f32_16x16x128_f8f6f4 v[220:223], v[140:147], v[90:97], v[14:17]
	v_mfma_f32_16x16x128_f8f6f4 v[224:227], v[148:155], v[90:97], v[10:13]
	v_mfma_f32_16x16x128_f8f6f4 v[54:57], v[156:163], v[66:73], v[54:57]
	v_mfma_f32_16x16x128_f8f6f4 v[50:53], v[164:171], v[66:73], v[50:53]
	v_mfma_f32_16x16x128_f8f6f4 v[228:231], v[156:163], v[74:81], v[38:41]
	v_mfma_f32_16x16x128_f8f6f4 v[232:235], v[164:171], v[74:81], v[34:37]
	v_mfma_f32_16x16x128_f8f6f4 v[236:239], v[156:163], v[82:89], v[22:25]
	v_mfma_f32_16x16x128_f8f6f4 v[246:249], v[164:171], v[82:89], v[18:21]
	v_mfma_f32_16x16x128_f8f6f4 v[250:253], v[156:163], v[90:97], v[6:9]
	v_mfma_f32_16x16x128_f8f6f4 v[240:243], v[164:171], v[90:97], v[2:5]
	s_barrier
	s_add_i32 s84, 0, 0x18000
	v_add_u32_e32 v0, s84, v138
	s_add_i32 s86, 0, 0x1c000
	s_nop 1
	ds_read_b128 v[2:5], v0
	ds_read_b128 v[6:9], v0 offset:1024
	ds_read_b128 v[18:21], v0 offset:2048
	ds_read_b128 v[22:25], v0 offset:3072
	v_add_u32_e32 v0, s86, v138
	ds_read_b128 v[140:143], v0
	ds_read_b128 v[144:147], v0 offset:1024
	ds_read_b128 v[148:151], v0 offset:2048
	ds_read_b128 v[152:155], v0 offset:3072
	s_add_i32 s83, s83, 0x80000
	ds_read_b128 v[10:13], v139 offset:32768
	ds_read_b128 v[14:17], v139 offset:33792
	ds_read_b128 v[26:29], v139 offset:34816
	ds_read_b128 v[30:33], v139 offset:35840
	ds_read_b128 v[34:37], v139 offset:36864
	ds_read_b128 v[38:41], v139 offset:37888
	ds_read_b128 v[42:45], v139 offset:38912
	ds_read_b128 v[46:49], v139 offset:39936
	s_mov_b32 m0, s12
	s_add_i32 vcc_lo, s83, 0x10000000
	s_add_u32 vcc_lo, s100, vcc_lo
	s_addc_u32 vcc_hi, s101, 0
	global_load_lds_dwordx4 v134, vcc
	s_mov_b32 m0, s13
	s_nop 0
	global_load_lds_dwordx4 v136, vcc
	s_waitcnt vmcnt(8)
	s_waitcnt lgkmcnt(0)
	s_barrier
	s_waitcnt lgkmcnt(0)
	v_mfma_f32_16x16x128_f8f6f4 v[126:129], v[2:9], v[10:17], v[126:129]
	v_mfma_f32_16x16x128_f8f6f4 v[122:125], v[18:25], v[10:17], v[122:125]
	v_mfma_f32_16x16x128_f8f6f4 v[110:113], v[2:9], v[26:33], v[110:113]
	v_mfma_f32_16x16x128_f8f6f4 v[106:109], v[18:25], v[26:33], v[106:109]
	v_mfma_f32_16x16x128_f8f6f4 v[94:97], v[2:9], v[34:41], v[204:207]
	v_mfma_f32_16x16x128_f8f6f4 v[90:93], v[18:25], v[34:41], v[208:211]
	v_mfma_f32_16x16x128_f8f6f4 v[78:81], v[2:9], v[42:49], v[212:215]
	v_mfma_f32_16x16x128_f8f6f4 v[74:77], v[18:25], v[42:49], v[216:219]
	v_mfma_f32_16x16x128_f8f6f4 v[118:121], v[140:147], v[10:17], v[118:121]
	v_mfma_f32_16x16x128_f8f6f4 v[114:117], v[148:155], v[10:17], v[114:117]
	v_mfma_f32_16x16x128_f8f6f4 v[102:105], v[140:147], v[26:33], v[102:105]
	v_mfma_f32_16x16x128_f8f6f4 v[98:101], v[148:155], v[26:33], v[98:101]
	v_mfma_f32_16x16x128_f8f6f4 v[86:89], v[140:147], v[34:41], v[172:175]
	v_mfma_f32_16x16x128_f8f6f4 v[82:85], v[148:155], v[34:41], v[176:179]
	v_mfma_f32_16x16x128_f8f6f4 v[70:73], v[140:147], v[42:49], v[180:183]
	v_mfma_f32_16x16x128_f8f6f4 v[66:69], v[148:155], v[42:49], v[184:187]
	s_barrier
	s_add_i32 s83, s47, 0x80
	ds_read_b128 v[34:37], v139 offset:49152
	ds_read_b128 v[38:41], v139 offset:50176
	ds_read_b128 v[156:159], v139 offset:51200
	ds_read_b128 v[160:163], v139 offset:52224
	ds_read_b128 v[164:167], v139 offset:53248
	ds_read_b128 v[168:171], v139 offset:54272
	ds_read_b128 v[172:175], v139 offset:55296
	ds_read_b128 v[176:179], v139 offset:56320
	s_add_i32 s84, s84, s7
	s_add_i32 vcc_lo, s83, 0x10000000
	s_add_u32 vcc_lo, s100, vcc_lo
	s_addc_u32 vcc_hi, s101, 0
	s_mov_b32 m0, s84
	s_nop 0
	global_load_lds_dwordx4 v135, vcc
	s_add_i32 m0, s84, 0x2000
	s_add_i32 s47, s47, 0x80080
	global_load_lds_dwordx4 v137, vcc
	s_add_i32 s83, s86, s7
	s_add_i32 vcc_lo, s47, 0x10000000
	s_add_u32 vcc_lo, s100, vcc_lo
	s_addc_u32 vcc_hi, s101, 0
	s_mov_b32 m0, s83
	s_nop 0
	global_load_lds_dwordx4 v135, vcc
	s_add_i32 m0, s83, 0x2000
	s_nop 0
	global_load_lds_dwordx4 v137, vcc
	s_mov_b32 m0, s18
	s_add_i32 vcc_lo, s82, 0x10000000
	s_add_u32 vcc_lo, s100, vcc_lo
	s_addc_u32 vcc_hi, s101, 0
	global_load_lds_dwordx4 v134, vcc
	s_mov_b32 m0, s22
	s_nop 0
	global_load_lds_dwordx4 v136, vcc
	s_waitcnt vmcnt(8)
	s_waitcnt lgkmcnt(0)
	s_barrier
; #define GAS __attribute__((address_space(1)))
; __device__ __forceinline__ unsigned gate_pk4(const f32x4& g) { return gate_q8(g[0]) | (gate_q8(g[1]) << 8) | (gate_q8(g[2]) << 16) | (gate_q8(g[3]) << 24); }
; #define PG8_STAGE(bufoff, gbase, voff) do { unsigned _g = (gbase); asm volatile("" : "+s"(_g));   _Pragma("unroll") for (int _i = 0; _i < 2; ++_i) \
;         __builtin_amdgcn_global_load_lds((const unsigned*)(wsb + (size_t)(unsigned)(_g + (voff)[_i])), (LAS unsigned*)(lds + (bufoff) + ldsw + _i * 8192), 16, 0, 0); } while (0)
; #define PG8_WAIT_V(n) asm volatile("s_waitcnt vmcnt(" #n ")" ::: "memory")
; #define PG8_WAIT_L(n) asm volatile("s_waitcnt lgkmcnt(" #n ")" ::: "memory")
; #define PG8_BAR __builtin_amdgcn_s_barrier()
; #define PG8_SCHED __builtin_amdgcn_sched_barrier(0)
;     ...
;             PG8_WAIT_V(8); PG8_WAIT_L(0); PG8_BAR; PG8_MMA(0, 0, At, B0); PG8_MMA(0, 1, At, B1); PG8_BAR; PG8_SCHED;
;             PG8_LDA(At, 1, 1); PG8_STAGE(PG8_SB(1, 0), b3, voffB); PG8_STAGE(PG8_SB(1, 1), b3 + hstep, voffB); PG8_STAGE(PG8_SA(1, 0), a3, voffA);
;             PG8_WAIT_V(8); PG8_WAIT_L(0); PG8_BAR; PG8_MMA(1, 0, At, B0); PG8_MMA(1, 1, At, B1); PG8_BAR; PG8_SCHED;
;     __device__ __forceinline__ void operator()(const f32x4 (&acc)[2][2][4][2], const pg8::GUnit& u, int wr, int wc, int fr, int fq) const {
;     ...
;         GAS unsigned char* gb = (GAS unsigned char*)P + (size_t)(u.pm * 256 + (wr * 4 + wc) * 32 + fq) * (INW * 2) + (GA * 2 + u.pn * 256 + fr * 16);
; #pragma unroll
;         for (int ai = 0; ai < 2; ++ai)
; #pragma unroll
;             for (int m = 0; m < 4; ++m) { u32x4 w; unsigned wq[4];
; #pragma unroll
;                 for (int bj = 0; bj < 2; ++bj)
; #pragma unroll
;                     for (int n = 0; n < 2; ++n) { f32x4 v = acc[ai][bj][m][n];
; #pragma unroll
;                         for (int j = 0; j < 4; ++j) v[j] = __builtin_amdgcn_rcpf(1.0f + __builtin_amdgcn_exp2f(v[j] * (-LOG2E * G8_DESCALE)));
;                         wq[bj * 2 + n] = gate_pk4(v); }
	s_waitcnt lgkmcnt(0)
	v_mfma_f32_16x16x128_f8f6f4 v[62:65], v[2:9], v[34:41], v[62:65]
	v_mfma_f32_16x16x128_f8f6f4 v[58:61], v[18:25], v[34:41], v[58:61]
	v_mfma_f32_16x16x128_f8f6f4 v[46:49], v[2:9], v[156:163], v[188:191]
	v_mfma_f32_16x16x128_f8f6f4 v[42:45], v[18:25], v[156:163], v[192:195]
	v_mfma_f32_16x16x128_f8f6f4 v[30:33], v[2:9], v[164:171], v[196:199]
	v_mfma_f32_16x16x128_f8f6f4 v[26:29], v[18:25], v[164:171], v[200:203]
	v_mfma_f32_16x16x128_f8f6f4 v[14:17], v[2:9], v[172:179], v[220:223]
	v_mfma_f32_16x16x128_f8f6f4 v[10:13], v[18:25], v[172:179], v[224:227]
	v_mfma_f32_16x16x128_f8f6f4 v[54:57], v[140:147], v[34:41], v[54:57]
	v_mfma_f32_16x16x128_f8f6f4 v[50:53], v[148:155], v[34:41], v[50:53]
	v_mfma_f32_16x16x128_f8f6f4 v[38:41], v[140:147], v[156:163], v[228:231]
	v_mfma_f32_16x16x128_f8f6f4 v[34:37], v[148:155], v[156:163], v[232:235]
	v_mfma_f32_16x16x128_f8f6f4 v[22:25], v[140:147], v[164:171], v[236:239]
	v_mfma_f32_16x16x128_f8f6f4 v[18:21], v[148:155], v[164:171], v[246:249]
	v_mfma_f32_16x16x128_f8f6f4 v[6:9], v[140:147], v[172:179], v[250:253]
	v_mfma_f32_16x16x128_f8f6f4 v[2:5], v[148:155], v[172:179], v[240:243]
	s_barrier
	s_add_i32 s46, s46, 2
	s_addk_i32 s44, 0x100
	s_addk_i32 s45, 0x100
	s_cmp_gt_u32 s46, 29
	s_cbranch_scc0 .LBB0_559
	s_setprio 0
	v_mbcnt_lo_u32_b32 v0, -1, 0
	v_mbcnt_hi_u32_b32 v0, -1, v0
	s_lshl_b32 s38, s38, 8
	v_ashrrev_i32_e32 v140, 4, v0
	v_lshlrev_b32_e32 v0, 4, v0
	s_addk_i32 s38, 0x6000
	v_and_b32_e32 v0, 0xf0, v0
	v_or_b32_e32 v142, s38, v0
	v_mul_f32_e32 v0, 0xba38aa3b, v126
	v_mul_f32_e32 v126, 0xba38aa3b, v127
	v_exp_f32_e32 v126, v126
	v_mul_f32_e32 v127, 0xba38aa3b, v128
	v_exp_f32_e32 v127, v127
	v_exp_f32_e32 v0, v0
	v_mul_f32_e32 v128, 0xba38aa3b, v129
	v_add_f32_e32 v126, 1.0, v126
	v_exp_f32_e32 v128, v128
	v_rcp_f32_e32 v126, v126
	v_add_f32_e32 v127, 1.0, v127
	v_add_f32_e32 v0, 1.0, v0
	v_rcp_f32_e32 v127, v127
	v_rcp_f32_e32 v0, v0
	v_add_f32_e32 v128, 1.0, v128
	v_rcp_f32_e32 v128, v128
	v_fma_f32 v126, v126, s49, 0.5
	v_max_f32_e32 v126, 1.0, v126
	v_cvt_u32_f32_e32 v129, v126
	v_fma_f32 v126, v127, s49, 0.5
	v_fma_f32 v0, v0, s49, 0.5
	v_max_f32_e32 v126, 1.0, v126
	v_max_f32_e32 v0, 1.0, v0
	v_cvt_u32_f32_sdwa v144, v126 dst_sel:WORD_1 dst_unused:UNUSED_PAD src0_sel:DWORD
	v_fma_f32 v126, v128, s49, 0.5
	v_cvt_u32_f32_e32 v0, v0
	v_max_f32_e32 v126, 1.0, v126
	v_mul_f32_e32 v122, 0xba38aa3b, v122
	v_mul_f32_e32 v123, 0xba38aa3b, v123
	v_cvt_u32_f32_sdwa v128, v126 dst_sel:BYTE_3 dst_unused:UNUSED_PAD src0_sel:DWORD
	v_exp_f32_e32 v145, v122
	v_exp_f32_e32 v123, v123
	v_lshl_or_b32 v0, v129, 8, v0
	v_or3_b32 v122, v0, v144, v128
	v_add_f32_e32 v0, 1.0, v145
	v_add_f32_e32 v123, 1.0, v123
	v_mul_f32_e32 v124, 0xba38aa3b, v124
	v_rcp_f32_e32 v0, v0
	v_rcp_f32_e32 v123, v123
	v_mul_f32_e32 v125, 0xba38aa3b, v125
	v_mul_f32_e32 v118, 0xba38aa3b, v118
	v_mul_f32_e32 v119, 0xba38aa3b, v119
	v_exp_f32_e32 v124, v124
	v_exp_f32_e32 v125, v125
	v_exp_f32_e32 v118, v118
	v_exp_f32_e32 v119, v119
	v_mul_f32_e32 v120, 0xba38aa3b, v120
	v_mul_f32_e32 v121, 0xba38aa3b, v121
	v_exp_f32_e32 v120, v120
	v_exp_f32_e32 v121, v121
	v_fma_f32 v0, v0, s49, 0.5
	v_fma_f32 v123, v123, s49, 0.5
	v_add_f32_e32 v124, 1.0, v124
	v_max_f32_e32 v0, 1.0, v0
	v_max_f32_e32 v123, 1.0, v123
	v_add_f32_e32 v125, 1.0, v125
	v_add_f32_e32 v118, 1.0, v118
	v_add_f32_e32 v119, 1.0, v119
	v_cvt_u32_f32_e32 v0, v0
	v_cvt_u32_f32_e32 v123, v123
	v_rcp_f32_e32 v124, v124
	v_rcp_f32_e32 v125, v125
	v_rcp_f32_e32 v118, v118
	v_rcp_f32_e32 v119, v119
	v_add_f32_e32 v120, 1.0, v120
	v_add_f32_e32 v121, 1.0, v121
	v_rcp_f32_e32 v120, v120
	v_rcp_f32_e32 v121, v121
	v_lshl_or_b32 v0, v123, 8, v0
	v_fma_f32 v123, v124, s49, 0.5
	v_fma_f32 v124, v125, s49, 0.5
	v_fma_f32 v118, v118, s49, 0.5
	v_fma_f32 v119, v119, s49, 0.5
	v_max_f32_e32 v123, 1.0, v123
	v_max_f32_e32 v124, 1.0, v124
	v_max_f32_e32 v118, 1.0, v118
	v_max_f32_e32 v119, 1.0, v119
	v_fma_f32 v120, v120, s49, 0.5
	v_fma_f32 v121, v121, s49, 0.5
	v_cvt_u32_f32_sdwa v123, v123 dst_sel:WORD_1 dst_unused:UNUSED_PAD src0_sel:DWORD
	v_cvt_u32_f32_sdwa v124, v124 dst_sel:BYTE_3 dst_unused:UNUSED_PAD src0_sel:DWORD
	v_cvt_u32_f32_e32 v118, v118
	v_cvt_u32_f32_e32 v119, v119
	v_max_f32_e32 v120, 1.0, v120
	v_max_f32_e32 v121, 1.0, v121
	v_mul_f32_e32 v114, 0xba38aa3b, v114
	v_cvt_u32_f32_sdwa v120, v120 dst_sel:WORD_1 dst_unused:UNUSED_PAD src0_sel:DWORD
	v_cvt_u32_f32_sdwa v121, v121 dst_sel:BYTE_3 dst_unused:UNUSED_PAD src0_sel:DWORD
	v_exp_f32_e32 v114, v114
	v_or3_b32 v123, v0, v123, v124
	v_lshl_or_b32 v0, v119, 8, v118
	v_or3_b32 v124, v0, v120, v121
	v_add_f32_e32 v0, 1.0, v114
	v_mul_f32_e32 v114, 0xba38aa3b, v115
	v_exp_f32_e32 v114, v114
	v_mul_f32_e32 v115, 0xba38aa3b, v116
	v_rcp_f32_e32 v0, v0
	v_mul_f32_e32 v116, 0xba38aa3b, v117
	v_add_f32_e32 v114, 1.0, v114
	v_rcp_f32_e32 v114, v114
	v_exp_f32_e32 v115, v115
	v_exp_f32_e32 v116, v116
	v_fma_f32 v0, v0, s49, 0.5
	v_fma_f32 v114, v114, s49, 0.5
	v_add_f32_e32 v115, 1.0, v115
	v_max_f32_e32 v0, 1.0, v0
	v_max_f32_e32 v114, 1.0, v114
	v_add_f32_e32 v116, 1.0, v116
	v_cvt_u32_f32_e32 v0, v0
	v_cvt_u32_f32_e32 v114, v114
	v_rcp_f32_e32 v115, v115
	v_rcp_f32_e32 v116, v116
	v_mul_f32_e32 v110, 0xba38aa3b, v110
	v_lshl_or_b32 v0, v114, 8, v0
	v_fma_f32 v114, v115, s49, 0.5
	v_fma_f32 v115, v116, s49, 0.5
	v_max_f32_e32 v114, 1.0, v114
	v_max_f32_e32 v115, 1.0, v115
	v_mul_f32_e32 v111, 0xba38aa3b, v111
	v_cvt_u32_f32_sdwa v114, v114 dst_sel:WORD_1 dst_unused:UNUSED_PAD src0_sel:DWORD
	v_cvt_u32_f32_sdwa v115, v115 dst_sel:BYTE_3 dst_unused:UNUSED_PAD src0_sel:DWORD
	v_exp_f32_e32 v110, v110
; __device__ __forceinline__ unsigned gate_q8(float g) { return (unsigned)fmaxf(g * 255.0f + 0.5f, 1.0f); }
; __device__ __forceinline__ unsigned gate_pk4(const f32x4& g) { return gate_q8(g[0]) | (gate_q8(g[1]) << 8) | (gate_q8(g[2]) << 16) | (gate_q8(g[3]) << 24); }
;     __device__ __forceinline__ void operator()(const f32x4 (&acc)[2][2][4][2], const pg8::GUnit& u, int wr, int wc, int fr, int fq) const {
;     ...
;                     for (int n = 0; n < 2; ++n) { f32x4 v = acc[ai][bj][m][n];
; #pragma unroll
;                         for (int j = 0; j < 4; ++j) v[j] = __builtin_amdgcn_rcpf(1.0f + __builtin_amdgcn_exp2f(v[j] * (-LOG2E * G8_DESCALE)));
;                         wq[bj * 2 + n] = gate_pk4(v); }
	v_exp_f32_e32 v111, v111
	v_mul_f32_e32 v106, 0xba38aa3b, v106
	v_or3_b32 v125, v0, v114, v115
	v_add_f32_e32 v0, 1.0, v110
	v_add_f32_e32 v110, 1.0, v111
	v_mul_f32_e32 v111, 0xba38aa3b, v112
	v_mul_f32_e32 v112, 0xba38aa3b, v113
	v_exp_f32_e32 v111, v111
	v_exp_f32_e32 v112, v112
	v_rcp_f32_e32 v0, v0
	v_rcp_f32_e32 v110, v110
	v_add_f32_e32 v111, 1.0, v111
	v_add_f32_e32 v112, 1.0, v112
	v_rcp_f32_e32 v111, v111
	v_rcp_f32_e32 v112, v112
	v_fma_f32 v0, v0, s49, 0.5
	v_fma_f32 v110, v110, s49, 0.5
	v_max_f32_e32 v0, 1.0, v0
	v_max_f32_e32 v110, 1.0, v110
	v_fma_f32 v111, v111, s49, 0.5
	v_fma_f32 v112, v112, s49, 0.5
	v_cvt_u32_f32_e32 v0, v0
	v_cvt_u32_f32_e32 v110, v110
	v_max_f32_e32 v111, 1.0, v111
	v_max_f32_e32 v112, 1.0, v112
	v_mul_f32_e32 v107, 0xba38aa3b, v107
	v_cvt_u32_f32_sdwa v111, v111 dst_sel:WORD_1 dst_unused:UNUSED_PAD src0_sel:DWORD
	v_cvt_u32_f32_sdwa v112, v112 dst_sel:BYTE_3 dst_unused:UNUSED_PAD src0_sel:DWORD
	v_exp_f32_e32 v113, v106
	v_exp_f32_e32 v107, v107
	v_lshl_or_b32 v0, v110, 8, v0
	v_or3_b32 v106, v0, v111, v112
	v_add_f32_e32 v0, 1.0, v113
	v_add_f32_e32 v107, 1.0, v107
	v_mul_f32_e32 v108, 0xba38aa3b, v108
	v_rcp_f32_e32 v0, v0
	v_rcp_f32_e32 v107, v107
	v_mul_f32_e32 v109, 0xba38aa3b, v109
	v_exp_f32_e32 v108, v108
	v_exp_f32_e32 v109, v109
	v_fma_f32 v0, v0, s49, 0.5
	v_fma_f32 v107, v107, s49, 0.5
	v_add_f32_e32 v108, 1.0, v108
	v_max_f32_e32 v0, 1.0, v0
	v_max_f32_e32 v107, 1.0, v107
	v_add_f32_e32 v109, 1.0, v109
	v_cvt_u32_f32_e32 v0, v0
	v_cvt_u32_f32_e32 v107, v107
	v_rcp_f32_e32 v108, v108
	v_rcp_f32_e32 v109, v109
	v_mul_f32_e32 v102, 0xba38aa3b, v102
	v_lshl_or_b32 v0, v107, 8, v0
	v_fma_f32 v107, v108, s49, 0.5
	v_fma_f32 v108, v109, s49, 0.5
	v_max_f32_e32 v107, 1.0, v107
	v_max_f32_e32 v108, 1.0, v108
	v_mul_f32_e32 v103, 0xba38aa3b, v103
	v_cvt_u32_f32_sdwa v107, v107 dst_sel:WORD_1 dst_unused:UNUSED_PAD src0_sel:DWORD
	v_cvt_u32_f32_sdwa v108, v108 dst_sel:BYTE_3 dst_unused:UNUSED_PAD src0_sel:DWORD
	v_exp_f32_e32 v102, v102
	v_exp_f32_e32 v103, v103
	v_mul_f32_e32 v98, 0xba38aa3b, v98
	v_or3_b32 v107, v0, v107, v108
	v_add_f32_e32 v0, 1.0, v102
	v_add_f32_e32 v102, 1.0, v103
	v_mul_f32_e32 v103, 0xba38aa3b, v104
	v_mul_f32_e32 v104, 0xba38aa3b, v105
	v_mul_f32_e32 v99, 0xba38aa3b, v99
	v_exp_f32_e32 v103, v103
	v_exp_f32_e32 v104, v104
	v_exp_f32_e32 v98, v98
	v_exp_f32_e32 v99, v99
	v_mul_f32_e32 v100, 0xba38aa3b, v100
	v_mul_f32_e32 v101, 0xba38aa3b, v101
	v_exp_f32_e32 v100, v100
	v_exp_f32_e32 v101, v101
	v_rcp_f32_e32 v0, v0
	v_rcp_f32_e32 v102, v102
	v_add_f32_e32 v103, 1.0, v103
	v_add_f32_e32 v104, 1.0, v104
	v_add_f32_e32 v98, 1.0, v98
	v_add_f32_e32 v99, 1.0, v99
	v_rcp_f32_e32 v103, v103
	v_rcp_f32_e32 v104, v104
	v_rcp_f32_e32 v98, v98
	v_rcp_f32_e32 v99, v99
	v_add_f32_e32 v100, 1.0, v100
	v_add_f32_e32 v101, 1.0, v101
	v_rcp_f32_e32 v100, v100
	v_rcp_f32_e32 v101, v101
	v_fma_f32 v0, v0, s49, 0.5
	v_fma_f32 v102, v102, s49, 0.5
	v_max_f32_e32 v0, 1.0, v0
	v_max_f32_e32 v102, 1.0, v102
	v_fma_f32 v103, v103, s49, 0.5
	v_fma_f32 v104, v104, s49, 0.5
	v_fma_f32 v98, v98, s49, 0.5
	v_fma_f32 v99, v99, s49, 0.5
	v_cvt_u32_f32_e32 v0, v0
	v_cvt_u32_f32_e32 v102, v102
	v_max_f32_e32 v103, 1.0, v103
	v_max_f32_e32 v104, 1.0, v104
	v_max_f32_e32 v98, 1.0, v98
	v_max_f32_e32 v99, 1.0, v99
	v_fma_f32 v100, v100, s49, 0.5
	v_fma_f32 v101, v101, s49, 0.5
	v_cvt_u32_f32_sdwa v103, v103 dst_sel:WORD_1 dst_unused:UNUSED_PAD src0_sel:DWORD
	v_cvt_u32_f32_sdwa v104, v104 dst_sel:BYTE_3 dst_unused:UNUSED_PAD src0_sel:DWORD
	v_cvt_u32_f32_e32 v98, v98
	v_cvt_u32_f32_e32 v99, v99
	v_max_f32_e32 v100, 1.0, v100
	v_max_f32_e32 v101, 1.0, v101
	v_cvt_u32_f32_sdwa v100, v100 dst_sel:WORD_1 dst_unused:UNUSED_PAD src0_sel:DWORD
	v_cvt_u32_f32_sdwa v101, v101 dst_sel:BYTE_3 dst_unused:UNUSED_PAD src0_sel:DWORD
	v_lshl_or_b32 v0, v102, 8, v0
	v_or3_b32 v108, v0, v103, v104
	v_lshl_or_b32 v0, v99, 8, v98
	v_or3_b32 v109, v0, v100, v101
	v_mul_f32_e32 v0, 0xba38aa3b, v94
	v_mul_f32_e32 v94, 0xba38aa3b, v95
	v_exp_f32_e32 v0, v0
	v_exp_f32_e32 v98, v94
	v_mul_f32_e32 v96, 0xba38aa3b, v96
	v_mul_f32_e32 v97, 0xba38aa3b, v97
	v_exp_f32_e32 v96, v96
	v_exp_f32_e32 v97, v97
	v_add_f32_e32 v0, 1.0, v0
	v_add_f32_e32 v98, 1.0, v98
	v_rcp_f32_e32 v0, v0
	v_rcp_f32_e32 v98, v98
	v_add_f32_e32 v96, 1.0, v96
	v_add_f32_e32 v97, 1.0, v97
	v_rcp_f32_e32 v96, v96
	v_rcp_f32_e32 v97, v97
	v_fma_f32 v0, v0, s49, 0.5
	v_fma_f32 v98, v98, s49, 0.5
	v_max_f32_e32 v0, 1.0, v0
	v_max_f32_e32 v98, 1.0, v98
	v_fma_f32 v96, v96, s49, 0.5
	v_fma_f32 v97, v97, s49, 0.5
	v_cvt_u32_f32_e32 v0, v0
	v_cvt_u32_f32_e32 v98, v98
	v_max_f32_e32 v96, 1.0, v96
	v_max_f32_e32 v97, 1.0, v97
	v_mul_f32_e32 v90, 0xba38aa3b, v90
	v_mul_f32_e32 v91, 0xba38aa3b, v91
	v_cvt_u32_f32_sdwa v96, v96 dst_sel:WORD_1 dst_unused:UNUSED_PAD src0_sel:DWORD
	v_cvt_u32_f32_sdwa v97, v97 dst_sel:BYTE_3 dst_unused:UNUSED_PAD src0_sel:DWORD
	v_exp_f32_e32 v99, v90
	v_exp_f32_e32 v91, v91
	v_lshl_or_b32 v0, v98, 8, v0
	v_or3_b32 v90, v0, v96, v97
	v_add_f32_e32 v0, 1.0, v99
	v_add_f32_e32 v91, 1.0, v91
	v_mul_f32_e32 v92, 0xba38aa3b, v92
	v_rcp_f32_e32 v0, v0
	v_rcp_f32_e32 v91, v91
	v_mul_f32_e32 v93, 0xba38aa3b, v93
	v_exp_f32_e32 v92, v92
	v_exp_f32_e32 v93, v93
	v_fma_f32 v0, v0, s49, 0.5
	v_fma_f32 v91, v91, s49, 0.5
	v_add_f32_e32 v92, 1.0, v92
	v_max_f32_e32 v0, 1.0, v0
	v_max_f32_e32 v91, 1.0, v91
	v_add_f32_e32 v93, 1.0, v93
	v_cvt_u32_f32_e32 v0, v0
	v_cvt_u32_f32_e32 v91, v91
	v_rcp_f32_e32 v92, v92
	v_rcp_f32_e32 v93, v93
	v_mul_f32_e32 v86, 0xba38aa3b, v86
	v_lshl_or_b32 v0, v91, 8, v0
	v_fma_f32 v91, v92, s49, 0.5
	v_fma_f32 v92, v93, s49, 0.5
; __device__ __forceinline__ unsigned gate_q8(float g) { return (unsigned)fmaxf(g * 255.0f + 0.5f, 1.0f); }
; __device__ __forceinline__ unsigned gate_pk4(const f32x4& g) { return gate_q8(g[0]) | (gate_q8(g[1]) << 8) | (gate_q8(g[2]) << 16) | (gate_q8(g[3]) << 24); }
;     __device__ __forceinline__ void operator()(const f32x4 (&acc)[2][2][4][2], const pg8::GUnit& u, int wr, int wc, int fr, int fq) const {
;     ...
;                         for (int j = 0; j < 4; ++j) v[j] = __builtin_amdgcn_rcpf(1.0f + __builtin_amdgcn_exp2f(v[j] * (-LOG2E * G8_DESCALE)));
;                         wq[bj * 2 + n] = gate_pk4(v); }
	v_max_f32_e32 v91, 1.0, v91
	v_max_f32_e32 v92, 1.0, v92
	v_mul_f32_e32 v87, 0xba38aa3b, v87
	v_cvt_u32_f32_sdwa v91, v91 dst_sel:WORD_1 dst_unused:UNUSED_PAD src0_sel:DWORD
	v_cvt_u32_f32_sdwa v92, v92 dst_sel:BYTE_3 dst_unused:UNUSED_PAD src0_sel:DWORD
	v_exp_f32_e32 v86, v86
	v_exp_f32_e32 v87, v87
	v_mul_f32_e32 v82, 0xba38aa3b, v82
	v_or3_b32 v91, v0, v91, v92
	v_add_f32_e32 v0, 1.0, v86
	v_add_f32_e32 v86, 1.0, v87
	v_mul_f32_e32 v87, 0xba38aa3b, v88
	v_mul_f32_e32 v88, 0xba38aa3b, v89
	v_mul_f32_e32 v83, 0xba38aa3b, v83
	v_exp_f32_e32 v87, v87
	v_exp_f32_e32 v88, v88
	v_exp_f32_e32 v82, v82
	v_exp_f32_e32 v83, v83
	v_mul_f32_e32 v84, 0xba38aa3b, v84
	v_mul_f32_e32 v85, 0xba38aa3b, v85
	v_exp_f32_e32 v84, v84
	v_exp_f32_e32 v85, v85
	v_rcp_f32_e32 v0, v0
	v_rcp_f32_e32 v86, v86
	v_add_f32_e32 v87, 1.0, v87
	v_add_f32_e32 v88, 1.0, v88
	v_add_f32_e32 v82, 1.0, v82
	v_add_f32_e32 v83, 1.0, v83
	v_rcp_f32_e32 v87, v87
	v_rcp_f32_e32 v88, v88
	v_rcp_f32_e32 v82, v82
	v_rcp_f32_e32 v83, v83
	v_add_f32_e32 v84, 1.0, v84
	v_add_f32_e32 v85, 1.0, v85
	v_rcp_f32_e32 v84, v84
	v_rcp_f32_e32 v85, v85
	v_fma_f32 v0, v0, s49, 0.5
	v_fma_f32 v86, v86, s49, 0.5
	v_max_f32_e32 v0, 1.0, v0
	v_max_f32_e32 v86, 1.0, v86
	v_fma_f32 v87, v87, s49, 0.5
	v_fma_f32 v88, v88, s49, 0.5
	v_fma_f32 v82, v82, s49, 0.5
	v_fma_f32 v83, v83, s49, 0.5
	v_cvt_u32_f32_e32 v0, v0
	v_cvt_u32_f32_e32 v86, v86
	v_max_f32_e32 v87, 1.0, v87
	v_max_f32_e32 v88, 1.0, v88
	v_max_f32_e32 v82, 1.0, v82
	v_max_f32_e32 v83, 1.0, v83
	v_fma_f32 v84, v84, s49, 0.5
	v_fma_f32 v85, v85, s49, 0.5
	v_cvt_u32_f32_sdwa v87, v87 dst_sel:WORD_1 dst_unused:UNUSED_PAD src0_sel:DWORD
	v_cvt_u32_f32_sdwa v88, v88 dst_sel:BYTE_3 dst_unused:UNUSED_PAD src0_sel:DWORD
	v_cvt_u32_f32_e32 v82, v82
	v_cvt_u32_f32_e32 v83, v83
	v_max_f32_e32 v84, 1.0, v84
	v_max_f32_e32 v85, 1.0, v85
	v_cvt_u32_f32_sdwa v84, v84 dst_sel:WORD_1 dst_unused:UNUSED_PAD src0_sel:DWORD
	v_cvt_u32_f32_sdwa v85, v85 dst_sel:BYTE_3 dst_unused:UNUSED_PAD src0_sel:DWORD
	v_lshl_or_b32 v0, v86, 8, v0
	v_or3_b32 v92, v0, v87, v88
	v_lshl_or_b32 v0, v83, 8, v82
	v_or3_b32 v93, v0, v84, v85
	v_mul_f32_e32 v0, 0xba38aa3b, v78
	v_mul_f32_e32 v78, 0xba38aa3b, v79
	v_exp_f32_e32 v0, v0
	v_exp_f32_e32 v82, v78
	v_mul_f32_e32 v80, 0xba38aa3b, v80
	v_mul_f32_e32 v81, 0xba38aa3b, v81
	v_exp_f32_e32 v80, v80
	v_exp_f32_e32 v81, v81
	v_add_f32_e32 v0, 1.0, v0
	v_add_f32_e32 v82, 1.0, v82
	v_rcp_f32_e32 v0, v0
	v_rcp_f32_e32 v82, v82
	v_add_f32_e32 v80, 1.0, v80
	v_add_f32_e32 v81, 1.0, v81
	v_rcp_f32_e32 v80, v80
	v_rcp_f32_e32 v81, v81
	v_fma_f32 v0, v0, s49, 0.5
	v_fma_f32 v82, v82, s49, 0.5
	v_max_f32_e32 v0, 1.0, v0
	v_max_f32_e32 v82, 1.0, v82
	v_fma_f32 v80, v80, s49, 0.5
	v_fma_f32 v81, v81, s49, 0.5
	v_cvt_u32_f32_e32 v0, v0
	v_cvt_u32_f32_e32 v82, v82
	v_max_f32_e32 v80, 1.0, v80
	v_max_f32_e32 v81, 1.0, v81
	v_mul_f32_e32 v74, 0xba38aa3b, v74
	v_mul_f32_e32 v75, 0xba38aa3b, v75
	v_cvt_u32_f32_sdwa v80, v80 dst_sel:WORD_1 dst_unused:UNUSED_PAD src0_sel:DWORD
	v_cvt_u32_f32_sdwa v81, v81 dst_sel:BYTE_3 dst_unused:UNUSED_PAD src0_sel:DWORD
	v_exp_f32_e32 v83, v74
	v_exp_f32_e32 v75, v75
	v_lshl_or_b32 v0, v82, 8, v0
	v_or3_b32 v74, v0, v80, v81
	v_add_f32_e32 v0, 1.0, v83
	v_add_f32_e32 v75, 1.0, v75
	v_mul_f32_e32 v76, 0xba38aa3b, v76
	v_rcp_f32_e32 v0, v0
	v_rcp_f32_e32 v75, v75
	v_mul_f32_e32 v77, 0xba38aa3b, v77
	v_exp_f32_e32 v76, v76
	v_exp_f32_e32 v77, v77
	v_fma_f32 v0, v0, s49, 0.5
	v_fma_f32 v75, v75, s49, 0.5
	v_add_f32_e32 v76, 1.0, v76
	v_max_f32_e32 v0, 1.0, v0
	v_max_f32_e32 v75, 1.0, v75
	v_add_f32_e32 v77, 1.0, v77
	v_cvt_u32_f32_e32 v0, v0
	v_cvt_u32_f32_e32 v75, v75
	v_rcp_f32_e32 v76, v76
	v_rcp_f32_e32 v77, v77
	v_mul_f32_e32 v70, 0xba38aa3b, v70
	v_lshl_or_b32 v0, v75, 8, v0
	v_fma_f32 v75, v76, s49, 0.5
	v_fma_f32 v76, v77, s49, 0.5
	v_max_f32_e32 v75, 1.0, v75
	v_max_f32_e32 v76, 1.0, v76
	v_mul_f32_e32 v71, 0xba38aa3b, v71
	v_cvt_u32_f32_sdwa v75, v75 dst_sel:WORD_1 dst_unused:UNUSED_PAD src0_sel:DWORD
	v_cvt_u32_f32_sdwa v76, v76 dst_sel:BYTE_3 dst_unused:UNUSED_PAD src0_sel:DWORD
	v_exp_f32_e32 v70, v70
	v_exp_f32_e32 v71, v71
	v_mul_f32_e32 v66, 0xba38aa3b, v66
	v_or3_b32 v75, v0, v75, v76
	v_add_f32_e32 v0, 1.0, v70
	v_add_f32_e32 v70, 1.0, v71
	v_mul_f32_e32 v71, 0xba38aa3b, v72
	v_mul_f32_e32 v72, 0xba38aa3b, v73
	v_mul_f32_e32 v67, 0xba38aa3b, v67
	v_exp_f32_e32 v71, v71
	v_exp_f32_e32 v72, v72
	v_exp_f32_e32 v66, v66
	v_exp_f32_e32 v67, v67
	v_mul_f32_e32 v68, 0xba38aa3b, v68
	v_mul_f32_e32 v69, 0xba38aa3b, v69
	v_exp_f32_e32 v68, v68
	v_exp_f32_e32 v69, v69
	v_rcp_f32_e32 v0, v0
	v_rcp_f32_e32 v70, v70
	v_add_f32_e32 v71, 1.0, v71
	v_add_f32_e32 v72, 1.0, v72
	v_add_f32_e32 v66, 1.0, v66
	v_add_f32_e32 v67, 1.0, v67
	v_rcp_f32_e32 v71, v71
	v_rcp_f32_e32 v72, v72
	v_rcp_f32_e32 v66, v66
	v_rcp_f32_e32 v67, v67
	v_add_f32_e32 v68, 1.0, v68
	v_add_f32_e32 v69, 1.0, v69
	v_rcp_f32_e32 v68, v68
	v_rcp_f32_e32 v69, v69
	v_fma_f32 v0, v0, s49, 0.5
	v_fma_f32 v70, v70, s49, 0.5
	v_max_f32_e32 v0, 1.0, v0
	v_max_f32_e32 v70, 1.0, v70
	v_fma_f32 v71, v71, s49, 0.5
	v_fma_f32 v72, v72, s49, 0.5
	v_fma_f32 v66, v66, s49, 0.5
	v_fma_f32 v67, v67, s49, 0.5
	v_cvt_u32_f32_e32 v0, v0
	v_cvt_u32_f32_e32 v70, v70
	v_max_f32_e32 v71, 1.0, v71
	v_max_f32_e32 v72, 1.0, v72
	v_max_f32_e32 v66, 1.0, v66
	v_max_f32_e32 v67, 1.0, v67
	v_fma_f32 v68, v68, s49, 0.5
	v_fma_f32 v69, v69, s49, 0.5
	v_cvt_u32_f32_sdwa v71, v71 dst_sel:WORD_1 dst_unused:UNUSED_PAD src0_sel:DWORD
	v_cvt_u32_f32_sdwa v72, v72 dst_sel:BYTE_3 dst_unused:UNUSED_PAD src0_sel:DWORD
	v_cvt_u32_f32_e32 v66, v66
	v_cvt_u32_f32_e32 v67, v67
; __device__ __forceinline__ unsigned gate_q8(float g) { return (unsigned)fmaxf(g * 255.0f + 0.5f, 1.0f); }
; __device__ __forceinline__ unsigned gate_pk4(const f32x4& g) { return gate_q8(g[0]) | (gate_q8(g[1]) << 8) | (gate_q8(g[2]) << 16) | (gate_q8(g[3]) << 24); }
;     __device__ __forceinline__ void operator()(const f32x4 (&acc)[2][2][4][2], const pg8::GUnit& u, int wr, int wc, int fr, int fq) const {
;     ...
;                         for (int j = 0; j < 4; ++j) v[j] = __builtin_amdgcn_rcpf(1.0f + __builtin_amdgcn_exp2f(v[j] * (-LOG2E * G8_DESCALE)));
;                         wq[bj * 2 + n] = gate_pk4(v); }
	v_max_f32_e32 v68, 1.0, v68
	v_max_f32_e32 v69, 1.0, v69
	v_cvt_u32_f32_sdwa v68, v68 dst_sel:WORD_1 dst_unused:UNUSED_PAD src0_sel:DWORD
	v_cvt_u32_f32_sdwa v69, v69 dst_sel:BYTE_3 dst_unused:UNUSED_PAD src0_sel:DWORD
	v_lshl_or_b32 v0, v70, 8, v0
	v_or3_b32 v76, v0, v71, v72
	v_lshl_or_b32 v0, v67, 8, v66
	v_or3_b32 v77, v0, v68, v69
	v_mul_f32_e32 v0, 0xba38aa3b, v62
	v_mul_f32_e32 v62, 0xba38aa3b, v63
	v_exp_f32_e32 v0, v0
	v_exp_f32_e32 v66, v62
	v_mul_f32_e32 v64, 0xba38aa3b, v64
	v_mul_f32_e32 v65, 0xba38aa3b, v65
	v_exp_f32_e32 v64, v64
	v_exp_f32_e32 v65, v65
	v_add_f32_e32 v0, 1.0, v0
	v_add_f32_e32 v66, 1.0, v66
	v_rcp_f32_e32 v0, v0
	v_rcp_f32_e32 v66, v66
	v_add_f32_e32 v64, 1.0, v64
	v_add_f32_e32 v65, 1.0, v65
	v_rcp_f32_e32 v64, v64
	v_rcp_f32_e32 v65, v65
	v_fma_f32 v0, v0, s49, 0.5
	v_fma_f32 v66, v66, s49, 0.5
	v_max_f32_e32 v0, 1.0, v0
	v_max_f32_e32 v66, 1.0, v66
	v_fma_f32 v64, v64, s49, 0.5
	v_fma_f32 v65, v65, s49, 0.5
	v_cvt_u32_f32_e32 v0, v0
	v_cvt_u32_f32_e32 v66, v66
	v_max_f32_e32 v64, 1.0, v64
	v_max_f32_e32 v65, 1.0, v65
	v_mul_f32_e32 v58, 0xba38aa3b, v58
	v_mul_f32_e32 v59, 0xba38aa3b, v59
	v_cvt_u32_f32_sdwa v64, v64 dst_sel:WORD_1 dst_unused:UNUSED_PAD src0_sel:DWORD
	v_cvt_u32_f32_sdwa v65, v65 dst_sel:BYTE_3 dst_unused:UNUSED_PAD src0_sel:DWORD
	v_exp_f32_e32 v67, v58
	v_exp_f32_e32 v59, v59
	v_lshl_or_b32 v0, v66, 8, v0
	v_or3_b32 v58, v0, v64, v65
	v_add_f32_e32 v0, 1.0, v67
	v_add_f32_e32 v59, 1.0, v59
	v_mul_f32_e32 v60, 0xba38aa3b, v60
	v_rcp_f32_e32 v0, v0
	v_rcp_f32_e32 v59, v59
	v_mul_f32_e32 v61, 0xba38aa3b, v61
	v_exp_f32_e32 v60, v60
	v_exp_f32_e32 v61, v61
	v_fma_f32 v0, v0, s49, 0.5
	v_fma_f32 v59, v59, s49, 0.5
	v_add_f32_e32 v60, 1.0, v60
	v_max_f32_e32 v0, 1.0, v0
	v_max_f32_e32 v59, 1.0, v59
	v_add_f32_e32 v61, 1.0, v61
	v_cvt_u32_f32_e32 v0, v0
	v_cvt_u32_f32_e32 v59, v59
	v_rcp_f32_e32 v60, v60
	v_rcp_f32_e32 v61, v61
	v_mul_f32_e32 v54, 0xba38aa3b, v54
	v_lshl_or_b32 v0, v59, 8, v0
	v_fma_f32 v59, v60, s49, 0.5
	v_fma_f32 v60, v61, s49, 0.5
	v_max_f32_e32 v59, 1.0, v59
	v_max_f32_e32 v60, 1.0, v60
	v_mul_f32_e32 v55, 0xba38aa3b, v55
	v_cvt_u32_f32_sdwa v59, v59 dst_sel:WORD_1 dst_unused:UNUSED_PAD src0_sel:DWORD
	v_cvt_u32_f32_sdwa v60, v60 dst_sel:BYTE_3 dst_unused:UNUSED_PAD src0_sel:DWORD
	v_exp_f32_e32 v54, v54
	v_exp_f32_e32 v55, v55
	v_mul_f32_e32 v50, 0xba38aa3b, v50
	v_or3_b32 v59, v0, v59, v60
	v_add_f32_e32 v0, 1.0, v54
	v_add_f32_e32 v54, 1.0, v55
	v_mul_f32_e32 v55, 0xba38aa3b, v56
	v_mul_f32_e32 v56, 0xba38aa3b, v57
	v_mul_f32_e32 v51, 0xba38aa3b, v51
	v_exp_f32_e32 v55, v55
	v_exp_f32_e32 v56, v56
	v_exp_f32_e32 v50, v50
	v_exp_f32_e32 v51, v51
	v_mul_f32_e32 v52, 0xba38aa3b, v52
	v_mul_f32_e32 v53, 0xba38aa3b, v53
	v_exp_f32_e32 v52, v52
	v_exp_f32_e32 v53, v53
	v_rcp_f32_e32 v0, v0
	v_rcp_f32_e32 v54, v54
	v_add_f32_e32 v55, 1.0, v55
	v_add_f32_e32 v56, 1.0, v56
	v_add_f32_e32 v50, 1.0, v50
	v_add_f32_e32 v51, 1.0, v51
	v_rcp_f32_e32 v55, v55
	v_rcp_f32_e32 v56, v56
	v_rcp_f32_e32 v50, v50
	v_rcp_f32_e32 v51, v51
	v_add_f32_e32 v52, 1.0, v52
	v_add_f32_e32 v53, 1.0, v53
	v_rcp_f32_e32 v52, v52
	v_rcp_f32_e32 v53, v53
	v_fma_f32 v0, v0, s49, 0.5
	v_fma_f32 v54, v54, s49, 0.5
	v_max_f32_e32 v0, 1.0, v0
	v_max_f32_e32 v54, 1.0, v54
	v_fma_f32 v55, v55, s49, 0.5
	v_fma_f32 v56, v56, s49, 0.5
	v_fma_f32 v50, v50, s49, 0.5
	v_fma_f32 v51, v51, s49, 0.5
	v_cvt_u32_f32_e32 v0, v0
	v_cvt_u32_f32_e32 v54, v54
	v_max_f32_e32 v55, 1.0, v55
	v_max_f32_e32 v56, 1.0, v56
	v_max_f32_e32 v50, 1.0, v50
	v_max_f32_e32 v51, 1.0, v51
	v_fma_f32 v52, v52, s49, 0.5
	v_fma_f32 v53, v53, s49, 0.5
	v_cvt_u32_f32_sdwa v55, v55 dst_sel:WORD_1 dst_unused:UNUSED_PAD src0_sel:DWORD
	v_cvt_u32_f32_sdwa v56, v56 dst_sel:BYTE_3 dst_unused:UNUSED_PAD src0_sel:DWORD
	v_cvt_u32_f32_e32 v50, v50
	v_cvt_u32_f32_e32 v51, v51
	v_max_f32_e32 v52, 1.0, v52
	v_max_f32_e32 v53, 1.0, v53
	v_cvt_u32_f32_sdwa v52, v52 dst_sel:WORD_1 dst_unused:UNUSED_PAD src0_sel:DWORD
	v_cvt_u32_f32_sdwa v53, v53 dst_sel:BYTE_3 dst_unused:UNUSED_PAD src0_sel:DWORD
	v_lshl_or_b32 v0, v54, 8, v0
	v_or3_b32 v60, v0, v55, v56
	v_lshl_or_b32 v0, v51, 8, v50
	v_or3_b32 v61, v0, v52, v53
	v_mul_f32_e32 v0, 0xba38aa3b, v46
	v_mul_f32_e32 v46, 0xba38aa3b, v47
	v_exp_f32_e32 v0, v0
	v_exp_f32_e32 v50, v46
	v_mul_f32_e32 v48, 0xba38aa3b, v48
	v_mul_f32_e32 v49, 0xba38aa3b, v49
	v_exp_f32_e32 v48, v48
	v_exp_f32_e32 v49, v49
	v_add_f32_e32 v0, 1.0, v0
	v_add_f32_e32 v50, 1.0, v50
	v_rcp_f32_e32 v0, v0
	v_rcp_f32_e32 v50, v50
	v_add_f32_e32 v48, 1.0, v48
	v_add_f32_e32 v49, 1.0, v49
	v_rcp_f32_e32 v48, v48
	v_rcp_f32_e32 v49, v49
	v_fma_f32 v0, v0, s49, 0.5
	v_fma_f32 v50, v50, s49, 0.5
	v_max_f32_e32 v0, 1.0, v0
	v_max_f32_e32 v50, 1.0, v50
	v_fma_f32 v48, v48, s49, 0.5
	v_fma_f32 v49, v49, s49, 0.5
	v_cvt_u32_f32_e32 v0, v0
	v_cvt_u32_f32_e32 v50, v50
	v_max_f32_e32 v48, 1.0, v48
	v_max_f32_e32 v49, 1.0, v49
	v_mul_f32_e32 v42, 0xba38aa3b, v42
	v_mul_f32_e32 v43, 0xba38aa3b, v43
	v_cvt_u32_f32_sdwa v48, v48 dst_sel:WORD_1 dst_unused:UNUSED_PAD src0_sel:DWORD
	v_cvt_u32_f32_sdwa v49, v49 dst_sel:BYTE_3 dst_unused:UNUSED_PAD src0_sel:DWORD
	v_exp_f32_e32 v51, v42
	v_exp_f32_e32 v43, v43
	v_lshl_or_b32 v0, v50, 8, v0
	v_or3_b32 v42, v0, v48, v49
	v_add_f32_e32 v0, 1.0, v51
	v_add_f32_e32 v43, 1.0, v43
	v_mul_f32_e32 v44, 0xba38aa3b, v44
	v_rcp_f32_e32 v0, v0
	v_rcp_f32_e32 v43, v43
	v_mul_f32_e32 v45, 0xba38aa3b, v45
	v_exp_f32_e32 v44, v44
	v_exp_f32_e32 v45, v45
	v_fma_f32 v0, v0, s49, 0.5
	v_fma_f32 v43, v43, s49, 0.5
	v_add_f32_e32 v44, 1.0, v44
	v_max_f32_e32 v0, 1.0, v0
	v_max_f32_e32 v43, 1.0, v43
	v_add_f32_e32 v45, 1.0, v45
; __device__ __forceinline__ unsigned gate_q8(float g) { return (unsigned)fmaxf(g * 255.0f + 0.5f, 1.0f); }
; __device__ __forceinline__ unsigned gate_pk4(const f32x4& g) { return gate_q8(g[0]) | (gate_q8(g[1]) << 8) | (gate_q8(g[2]) << 16) | (gate_q8(g[3]) << 24); }
;     __device__ __forceinline__ void operator()(const f32x4 (&acc)[2][2][4][2], const pg8::GUnit& u, int wr, int wc, int fr, int fq) const {
;     ...
;                         for (int j = 0; j < 4; ++j) v[j] = __builtin_amdgcn_rcpf(1.0f + __builtin_amdgcn_exp2f(v[j] * (-LOG2E * G8_DESCALE)));
;                         wq[bj * 2 + n] = gate_pk4(v); }
	v_cvt_u32_f32_e32 v0, v0
	v_cvt_u32_f32_e32 v43, v43
	v_rcp_f32_e32 v44, v44
	v_rcp_f32_e32 v45, v45
	v_mul_f32_e32 v38, 0xba38aa3b, v38
	v_lshl_or_b32 v0, v43, 8, v0
	v_fma_f32 v43, v44, s49, 0.5
	v_fma_f32 v44, v45, s49, 0.5
	v_max_f32_e32 v43, 1.0, v43
	v_max_f32_e32 v44, 1.0, v44
	v_mul_f32_e32 v39, 0xba38aa3b, v39
	v_cvt_u32_f32_sdwa v43, v43 dst_sel:WORD_1 dst_unused:UNUSED_PAD src0_sel:DWORD
	v_cvt_u32_f32_sdwa v44, v44 dst_sel:BYTE_3 dst_unused:UNUSED_PAD src0_sel:DWORD
	v_exp_f32_e32 v38, v38
	v_exp_f32_e32 v39, v39
	v_mul_f32_e32 v34, 0xba38aa3b, v34
	v_or3_b32 v43, v0, v43, v44
	v_add_f32_e32 v0, 1.0, v38
	v_add_f32_e32 v38, 1.0, v39
	v_mul_f32_e32 v39, 0xba38aa3b, v40
	v_mul_f32_e32 v40, 0xba38aa3b, v41
	v_mul_f32_e32 v35, 0xba38aa3b, v35
	v_exp_f32_e32 v39, v39
	v_exp_f32_e32 v40, v40
	v_exp_f32_e32 v34, v34
	v_exp_f32_e32 v35, v35
	v_mul_f32_e32 v36, 0xba38aa3b, v36
	v_mul_f32_e32 v37, 0xba38aa3b, v37
	v_exp_f32_e32 v36, v36
	v_exp_f32_e32 v37, v37
	v_rcp_f32_e32 v0, v0
	v_rcp_f32_e32 v38, v38
	v_add_f32_e32 v39, 1.0, v39
	v_add_f32_e32 v40, 1.0, v40
	v_add_f32_e32 v34, 1.0, v34
	v_add_f32_e32 v35, 1.0, v35
	v_rcp_f32_e32 v39, v39
	v_rcp_f32_e32 v40, v40
	v_rcp_f32_e32 v34, v34
	v_rcp_f32_e32 v35, v35
	v_add_f32_e32 v36, 1.0, v36
	v_add_f32_e32 v37, 1.0, v37
	v_rcp_f32_e32 v36, v36
	v_rcp_f32_e32 v37, v37
	v_fma_f32 v0, v0, s49, 0.5
	v_fma_f32 v38, v38, s49, 0.5
	v_max_f32_e32 v0, 1.0, v0
	v_max_f32_e32 v38, 1.0, v38
	v_fma_f32 v39, v39, s49, 0.5
	v_fma_f32 v40, v40, s49, 0.5
	v_fma_f32 v34, v34, s49, 0.5
	v_fma_f32 v35, v35, s49, 0.5
	v_cvt_u32_f32_e32 v0, v0
	v_cvt_u32_f32_e32 v38, v38
	v_max_f32_e32 v39, 1.0, v39
	v_max_f32_e32 v40, 1.0, v40
	v_max_f32_e32 v34, 1.0, v34
	v_max_f32_e32 v35, 1.0, v35
	v_fma_f32 v36, v36, s49, 0.5
	v_fma_f32 v37, v37, s49, 0.5
	v_cvt_u32_f32_sdwa v39, v39 dst_sel:WORD_1 dst_unused:UNUSED_PAD src0_sel:DWORD
	v_cvt_u32_f32_sdwa v40, v40 dst_sel:BYTE_3 dst_unused:UNUSED_PAD src0_sel:DWORD
	v_cvt_u32_f32_e32 v34, v34
	v_cvt_u32_f32_e32 v35, v35
	v_max_f32_e32 v36, 1.0, v36
	v_max_f32_e32 v37, 1.0, v37
	v_cvt_u32_f32_sdwa v36, v36 dst_sel:WORD_1 dst_unused:UNUSED_PAD src0_sel:DWORD
	v_cvt_u32_f32_sdwa v37, v37 dst_sel:BYTE_3 dst_unused:UNUSED_PAD src0_sel:DWORD
	v_lshl_or_b32 v0, v38, 8, v0
	v_or3_b32 v44, v0, v39, v40
	v_lshl_or_b32 v0, v35, 8, v34
	v_or3_b32 v45, v0, v36, v37
	v_mul_f32_e32 v0, 0xba38aa3b, v30
	v_mul_f32_e32 v30, 0xba38aa3b, v31
	v_exp_f32_e32 v0, v0
	v_exp_f32_e32 v34, v30
	v_mul_f32_e32 v32, 0xba38aa3b, v32
	v_mul_f32_e32 v33, 0xba38aa3b, v33
	v_exp_f32_e32 v32, v32
	v_exp_f32_e32 v33, v33
	v_add_f32_e32 v0, 1.0, v0
	v_add_f32_e32 v34, 1.0, v34
	v_rcp_f32_e32 v0, v0
	v_rcp_f32_e32 v34, v34
	v_add_f32_e32 v32, 1.0, v32
	v_add_f32_e32 v33, 1.0, v33
	v_rcp_f32_e32 v32, v32
	v_rcp_f32_e32 v33, v33
	v_fma_f32 v0, v0, s49, 0.5
	v_fma_f32 v34, v34, s49, 0.5
	v_max_f32_e32 v0, 1.0, v0
	v_max_f32_e32 v34, 1.0, v34
	v_fma_f32 v32, v32, s49, 0.5
	v_fma_f32 v33, v33, s49, 0.5
	v_cvt_u32_f32_e32 v0, v0
	v_cvt_u32_f32_e32 v34, v34
	v_max_f32_e32 v32, 1.0, v32
	v_max_f32_e32 v33, 1.0, v33
	v_mul_f32_e32 v26, 0xba38aa3b, v26
	v_mul_f32_e32 v27, 0xba38aa3b, v27
	v_cvt_u32_f32_sdwa v32, v32 dst_sel:WORD_1 dst_unused:UNUSED_PAD src0_sel:DWORD
	v_cvt_u32_f32_sdwa v33, v33 dst_sel:BYTE_3 dst_unused:UNUSED_PAD src0_sel:DWORD
	v_exp_f32_e32 v35, v26
	v_exp_f32_e32 v27, v27
	v_lshl_or_b32 v0, v34, 8, v0
	v_or3_b32 v26, v0, v32, v33
	v_add_f32_e32 v0, 1.0, v35
	v_add_f32_e32 v27, 1.0, v27
	v_mul_f32_e32 v28, 0xba38aa3b, v28
	v_rcp_f32_e32 v0, v0
	v_rcp_f32_e32 v27, v27
	v_mul_f32_e32 v29, 0xba38aa3b, v29
	v_exp_f32_e32 v28, v28
	v_exp_f32_e32 v29, v29
	v_fma_f32 v0, v0, s49, 0.5
	v_fma_f32 v27, v27, s49, 0.5
	v_add_f32_e32 v28, 1.0, v28
	v_max_f32_e32 v0, 1.0, v0
	v_max_f32_e32 v27, 1.0, v27
	v_add_f32_e32 v29, 1.0, v29
	v_cvt_u32_f32_e32 v0, v0
	v_cvt_u32_f32_e32 v27, v27
	v_rcp_f32_e32 v28, v28
	v_rcp_f32_e32 v29, v29
	v_mul_f32_e32 v22, 0xba38aa3b, v22
	v_lshl_or_b32 v0, v27, 8, v0
	v_fma_f32 v27, v28, s49, 0.5
	v_fma_f32 v28, v29, s49, 0.5
	v_max_f32_e32 v27, 1.0, v27
	v_max_f32_e32 v28, 1.0, v28
	v_mul_f32_e32 v23, 0xba38aa3b, v23
	v_cvt_u32_f32_sdwa v27, v27 dst_sel:WORD_1 dst_unused:UNUSED_PAD src0_sel:DWORD
	v_cvt_u32_f32_sdwa v28, v28 dst_sel:BYTE_3 dst_unused:UNUSED_PAD src0_sel:DWORD
	v_exp_f32_e32 v22, v22
	v_exp_f32_e32 v23, v23
	v_mul_f32_e32 v18, 0xba38aa3b, v18
	v_or3_b32 v27, v0, v27, v28
	v_add_f32_e32 v0, 1.0, v22
	v_add_f32_e32 v22, 1.0, v23
	v_mul_f32_e32 v23, 0xba38aa3b, v24
	v_mul_f32_e32 v24, 0xba38aa3b, v25
	v_mul_f32_e32 v19, 0xba38aa3b, v19
	v_exp_f32_e32 v23, v23
	v_exp_f32_e32 v24, v24
	v_exp_f32_e32 v18, v18
	v_exp_f32_e32 v19, v19
	v_mul_f32_e32 v20, 0xba38aa3b, v20
	v_mul_f32_e32 v21, 0xba38aa3b, v21
	v_exp_f32_e32 v20, v20
	v_exp_f32_e32 v21, v21
	v_rcp_f32_e32 v0, v0
	v_rcp_f32_e32 v22, v22
	v_add_f32_e32 v23, 1.0, v23
	v_add_f32_e32 v24, 1.0, v24
	v_add_f32_e32 v18, 1.0, v18
	v_add_f32_e32 v19, 1.0, v19
	v_rcp_f32_e32 v23, v23
	v_rcp_f32_e32 v24, v24
	v_rcp_f32_e32 v18, v18
	v_rcp_f32_e32 v19, v19
	v_add_f32_e32 v20, 1.0, v20
	v_add_f32_e32 v21, 1.0, v21
	v_rcp_f32_e32 v20, v20
	v_rcp_f32_e32 v21, v21
	v_fma_f32 v0, v0, s49, 0.5
	v_fma_f32 v22, v22, s49, 0.5
	v_max_f32_e32 v0, 1.0, v0
	v_max_f32_e32 v22, 1.0, v22
	v_fma_f32 v23, v23, s49, 0.5
	v_fma_f32 v24, v24, s49, 0.5
	v_fma_f32 v18, v18, s49, 0.5
	v_fma_f32 v19, v19, s49, 0.5
	v_cvt_u32_f32_e32 v0, v0
	v_cvt_u32_f32_e32 v22, v22
	v_max_f32_e32 v23, 1.0, v23
	v_max_f32_e32 v24, 1.0, v24
	v_max_f32_e32 v18, 1.0, v18
	v_max_f32_e32 v19, 1.0, v19
	v_fma_f32 v20, v20, s49, 0.5
	v_fma_f32 v21, v21, s49, 0.5
; #define GAS __attribute__((address_space(1)))
; __device__ __forceinline__ unsigned gate_pk4(const f32x4& g) { return gate_q8(g[0]) | (gate_q8(g[1]) << 8) | (gate_q8(g[2]) << 16) | (gate_q8(g[3]) << 24); }
; #define PG8_WAIT_V(n) asm volatile("s_waitcnt vmcnt(" #n ")" ::: "memory")
; #define PG8_BAR __builtin_amdgcn_s_barrier()
;     ...
;         if (!has_next) break;
; #pragma unroll
;         for (int a = 0; a < 2; ++a)
; #pragma unroll
;             for (int b = 0; b < 2; ++b)
; #pragma unroll
;                 for (int m = 0; m < 4; ++m)
; #pragma unroll
;                     for (int n = 0; n < 2; ++n) acc[a][b][m][n] = (f32x4){0.f, 0.f, 0.f, 0.f};
;         cur = nxt; cA = nA; cB = nB; ++ui;
;     }
;     PG8_WAIT_V(0);
;     if (wr == 0) PG8_BAR;
;     __device__ __forceinline__ void operator()(const f32x4 (&acc)[2][2][4][2], const pg8::GUnit& u, int wr, int wc, int fr, int fq) const {
;     ...
;         GAS unsigned char* gb = (GAS unsigned char*)P + (size_t)(u.pm * 256 + (wr * 4 + wc) * 32 + fq) * (INW * 2) + (GA * 2 + u.pn * 256 + fr * 16);
; #pragma unroll
;         for (int ai = 0; ai < 2; ++ai)
; #pragma unroll
;             for (int m = 0; m < 4; ++m) { u32x4 w; unsigned wq[4];
; #pragma unroll
;                 for (int bj = 0; bj < 2; ++bj)
; #pragma unroll
;                     for (int n = 0; n < 2; ++n) { f32x4 v = acc[ai][bj][m][n];
; #pragma unroll
;                         for (int j = 0; j < 4; ++j) v[j] = __builtin_amdgcn_rcpf(1.0f + __builtin_amdgcn_exp2f(v[j] * (-LOG2E * G8_DESCALE)));
;                         wq[bj * 2 + n] = gate_pk4(v); }
;                 w.x = wq[0]; w.y = wq[1]; w.z = wq[2]; w.w = wq[3];
;                 *(GAS u32x4*)(gb + (size_t)((ai * 4 + m) * 4) * (INW * 2)) = w; }
	v_cvt_u32_f32_sdwa v23, v23 dst_sel:WORD_1 dst_unused:UNUSED_PAD src0_sel:DWORD
	v_cvt_u32_f32_sdwa v24, v24 dst_sel:BYTE_3 dst_unused:UNUSED_PAD src0_sel:DWORD
	v_cvt_u32_f32_e32 v18, v18
	v_cvt_u32_f32_e32 v19, v19
	v_max_f32_e32 v20, 1.0, v20
	v_max_f32_e32 v21, 1.0, v21
	v_cvt_u32_f32_sdwa v20, v20 dst_sel:WORD_1 dst_unused:UNUSED_PAD src0_sel:DWORD
	v_cvt_u32_f32_sdwa v21, v21 dst_sel:BYTE_3 dst_unused:UNUSED_PAD src0_sel:DWORD
	v_lshl_or_b32 v0, v22, 8, v0
	v_or3_b32 v28, v0, v23, v24
	v_lshl_or_b32 v0, v19, 8, v18
	v_or3_b32 v29, v0, v20, v21
	v_mul_f32_e32 v0, 0xba38aa3b, v14
	v_mul_f32_e32 v14, 0xba38aa3b, v15
	v_exp_f32_e32 v0, v0
	v_exp_f32_e32 v18, v14
	v_mul_f32_e32 v16, 0xba38aa3b, v16
	v_mul_f32_e32 v17, 0xba38aa3b, v17
	v_exp_f32_e32 v16, v16
	v_exp_f32_e32 v17, v17
	v_add_f32_e32 v0, 1.0, v0
	v_add_f32_e32 v18, 1.0, v18
	v_rcp_f32_e32 v0, v0
	v_rcp_f32_e32 v18, v18
	v_add_f32_e32 v16, 1.0, v16
	v_add_f32_e32 v17, 1.0, v17
	v_rcp_f32_e32 v16, v16
	v_rcp_f32_e32 v17, v17
	v_fma_f32 v0, v0, s49, 0.5
	v_fma_f32 v18, v18, s49, 0.5
	v_max_f32_e32 v0, 1.0, v0
	v_max_f32_e32 v18, 1.0, v18
	v_fma_f32 v16, v16, s49, 0.5
	v_fma_f32 v17, v17, s49, 0.5
	v_cvt_u32_f32_e32 v0, v0
	v_cvt_u32_f32_e32 v18, v18
	v_max_f32_e32 v16, 1.0, v16
	v_max_f32_e32 v17, 1.0, v17
	v_mul_f32_e32 v10, 0xba38aa3b, v10
	v_mul_f32_e32 v11, 0xba38aa3b, v11
	v_cvt_u32_f32_sdwa v16, v16 dst_sel:WORD_1 dst_unused:UNUSED_PAD src0_sel:DWORD
	v_cvt_u32_f32_sdwa v17, v17 dst_sel:BYTE_3 dst_unused:UNUSED_PAD src0_sel:DWORD
	v_exp_f32_e32 v19, v10
	v_exp_f32_e32 v11, v11
	v_lshl_or_b32 v0, v18, 8, v0
	v_or3_b32 v10, v0, v16, v17
	v_add_f32_e32 v0, 1.0, v19
	v_add_f32_e32 v11, 1.0, v11
	v_mul_f32_e32 v12, 0xba38aa3b, v12
	v_rcp_f32_e32 v0, v0
	v_rcp_f32_e32 v11, v11
	v_mul_f32_e32 v13, 0xba38aa3b, v13
	v_exp_f32_e32 v12, v12
	v_exp_f32_e32 v13, v13
	v_fma_f32 v0, v0, s49, 0.5
	v_fma_f32 v11, v11, s49, 0.5
	v_add_f32_e32 v12, 1.0, v12
	v_max_f32_e32 v0, 1.0, v0
	v_max_f32_e32 v11, 1.0, v11
	v_add_f32_e32 v13, 1.0, v13
	v_cvt_u32_f32_e32 v0, v0
	v_cvt_u32_f32_e32 v11, v11
	v_rcp_f32_e32 v12, v12
	v_rcp_f32_e32 v13, v13
	v_mul_f32_e32 v6, 0xba38aa3b, v6
	v_lshl_or_b32 v0, v11, 8, v0
	v_fma_f32 v11, v12, s49, 0.5
	v_fma_f32 v12, v13, s49, 0.5
	v_max_f32_e32 v11, 1.0, v11
	v_max_f32_e32 v12, 1.0, v12
	v_mul_f32_e32 v7, 0xba38aa3b, v7
	v_cvt_u32_f32_sdwa v11, v11 dst_sel:WORD_1 dst_unused:UNUSED_PAD src0_sel:DWORD
	v_cvt_u32_f32_sdwa v12, v12 dst_sel:BYTE_3 dst_unused:UNUSED_PAD src0_sel:DWORD
	v_exp_f32_e32 v6, v6
	v_exp_f32_e32 v7, v7
	s_lshl_b32 s39, s39, 8
	s_add_i32 s39, s40, s39
	v_or3_b32 v11, v0, v11, v12
	v_add_f32_e32 v0, 1.0, v6
	v_add_f32_e32 v6, 1.0, v7
	v_mul_f32_e32 v7, 0xba38aa3b, v8
	v_mul_f32_e32 v8, 0xba38aa3b, v9
	v_mul_f32_e32 v2, 0xba38aa3b, v2
	v_mul_f32_e32 v3, 0xba38aa3b, v3
	v_add_u32_e32 v140, s39, v140
	v_exp_f32_e32 v7, v7
	v_exp_f32_e32 v8, v8
	v_exp_f32_e32 v2, v2
	v_exp_f32_e32 v3, v3
	v_mad_i64_i32 v[140:141], s[44:45], v140, s93, v[132:133]
	v_ashrrev_i32_e32 v143, 31, v142
	v_mul_f32_e32 v4, 0xba38aa3b, v4
	v_mul_f32_e32 v5, 0xba38aa3b, v5
	v_lshl_add_u64 v[126:127], v[140:141], 0, v[142:143]
	v_exp_f32_e32 v4, v4
	v_exp_f32_e32 v5, v5
	v_add_co_u32_e32 v94, vcc, s48, v126
	v_rcp_f32_e32 v0, v0
	s_nop 0
	v_addc_co_u32_e32 v95, vcc, 0, v127, vcc
	v_rcp_f32_e32 v6, v6
	v_add_f32_e32 v7, 1.0, v7
	v_add_f32_e32 v8, 1.0, v8
	v_add_f32_e32 v2, 1.0, v2
	v_add_f32_e32 v3, 1.0, v3
	v_add_co_u32_e32 v78, vcc, s26, v126
	v_rcp_f32_e32 v7, v7
	v_rcp_f32_e32 v8, v8
	v_rcp_f32_e32 v2, v2
	v_rcp_f32_e32 v3, v3
	v_addc_co_u32_e32 v79, vcc, 0, v127, vcc
	s_mov_b32 s38, 0x90000
	v_add_f32_e32 v4, 1.0, v4
	v_add_f32_e32 v5, 1.0, v5
	v_add_co_u32_e32 v62, vcc, s38, v126
	v_rcp_f32_e32 v4, v4
	v_rcp_f32_e32 v5, v5
	v_addc_co_u32_e32 v63, vcc, 0, v127, vcc
	s_mov_b32 s38, 0xc0000
	v_fma_f32 v0, v0, s49, 0.5
	v_fma_f32 v6, v6, s49, 0.5
	v_add_co_u32_e32 v46, vcc, s38, v126
	v_max_f32_e32 v0, 1.0, v0
	v_max_f32_e32 v6, 1.0, v6
	v_fma_f32 v7, v7, s49, 0.5
	v_fma_f32 v8, v8, s49, 0.5
	v_fma_f32 v2, v2, s49, 0.5
	v_fma_f32 v3, v3, s49, 0.5
	v_addc_co_u32_e32 v47, vcc, 0, v127, vcc
	s_mov_b32 s38, 0xf0000
	v_cvt_u32_f32_e32 v0, v0
	v_cvt_u32_f32_e32 v6, v6
	v_max_f32_e32 v7, 1.0, v7
	v_max_f32_e32 v8, 1.0, v8
	v_max_f32_e32 v2, 1.0, v2
	v_max_f32_e32 v3, 1.0, v3
	v_add_co_u32_e32 v30, vcc, s38, v126
	v_cvt_u32_f32_sdwa v7, v7 dst_sel:WORD_1 dst_unused:UNUSED_PAD src0_sel:DWORD
	v_cvt_u32_f32_sdwa v8, v8 dst_sel:BYTE_3 dst_unused:UNUSED_PAD src0_sel:DWORD
	v_cvt_u32_f32_e32 v2, v2
	v_cvt_u32_f32_e32 v3, v3
	v_fma_f32 v4, v4, s49, 0.5
	v_fma_f32 v5, v5, s49, 0.5
	v_addc_co_u32_e32 v31, vcc, 0, v127, vcc
	v_max_f32_e32 v4, 1.0, v4
	v_max_f32_e32 v5, 1.0, v5
	v_add_co_u32_e32 v14, vcc, s27, v126
	v_cvt_u32_f32_sdwa v4, v4 dst_sel:WORD_1 dst_unused:UNUSED_PAD src0_sel:DWORD
	v_cvt_u32_f32_sdwa v5, v5 dst_sel:BYTE_3 dst_unused:UNUSED_PAD src0_sel:DWORD
	v_addc_co_u32_e32 v15, vcc, 0, v127, vcc
	v_lshl_or_b32 v0, v6, 8, v0
	v_or3_b32 v12, v0, v7, v8
	v_lshl_or_b32 v0, v3, 8, v2
	v_add_co_u32_e32 v2, vcc, 0x150000, v126
	v_or3_b32 v13, v0, v4, v5
	s_nop 0
	v_addc_co_u32_e32 v3, vcc, 0, v127, vcc
	s_and_b64 vcc, exec, s[4:5]
	s_mov_b32 s39, s25
	s_mov_b32 s38, s24
	s_mov_b32 s45, s37
	s_mov_b32 s44, s36
	global_store_dwordx4 v[126:127], v[122:125], off
	global_store_dwordx4 v[94:95], v[106:109], off
	global_store_dwordx4 v[78:79], v[90:93], off
	global_store_dwordx4 v[62:63], v[74:77], off
	global_store_dwordx4 v[46:47], v[58:61], off
	global_store_dwordx4 v[30:31], v[42:45], off
	global_store_dwordx4 v[14:15], v[26:29], off
	global_store_dwordx4 v[2:3], v[10:13], off
	s_cbranch_vccz .LBB0_556
	v_readlane_b32 s4, v255, 6
	s_waitcnt vmcnt(0)
	v_readlane_b32 s5, v255, 7
	s_andn2_b64 vcc, exec, s[4:5]
	s_cbranch_vccnz .LBB0_563
	s_barrier

; __device__ __forceinline__ int lane_id_hw() { int l; asm volatile("v_mbcnt_lo_u32_b32 %0, -1, 0\n\tv_mbcnt_hi_u32_b32 %0, -1, %0" : "=v"(l)); return l; }
; #define PG8_STAGE(bufoff, gbase, voff) do { unsigned _g = (gbase); asm volatile("" : "+s"(_g));   _Pragma("unroll") for (int _i = 0; _i < 2; ++_i) \
;         __builtin_amdgcn_global_load_lds((const unsigned*)(wsb + (size_t)(unsigned)(_g + (voff)[_i])), (LAS unsigned*)(lds + (bufoff) + ldsw + _i * 8192), 16, 0, 0); } while (0)
; #define PG8_WAIT_V(n) asm volatile("s_waitcnt vmcnt(" #n ")" ::: "memory")
; #define PG8_WAIT_L(n) asm volatile("s_waitcnt lgkmcnt(" #n ")" ::: "memory")
; #define PG8_BAR __builtin_amdgcn_s_barrier()
; #define PG8_SCHED __builtin_amdgcn_sched_barrier(0)
;     ...
;         for (int t = 0; t < nt; t += 2) {
;             if constexpr (Epi::HAS_MID) { if (t == Epi::MID0 || t == Epi::MID1) { const int l2 = lane_id_hw(); E.mid(acc, cur, t == Epi::MID0 ? 0 : 1, wr, wc, l2 & 15, l2 >> 4); } }
;             const bool last = (t == nt - 2);
;             const unsigned a1 = cA + (unsigned)(t + 1) * kstep;
;             const unsigned a2 = last ? nA : cA + (unsigned)(t + 2) * kstep, b2 = last ? nB : cB + (unsigned)(t + 2) * kstep;
;             const unsigned a3 = a2 + kstep, b3 = b2 + kstep;
;             if constexpr (SP2) {
;             PG8_LDB(B0, 0, 0); PG8_LDB(B1, 0, 1); PG8_SCHED; PG8_LDA(At, 0, 0); PG8_STAGE(PG8_SA(1, 1), a1 + hstep, voffA);
;             PG8_WAIT_V(8); PG8_WAIT_L(0); PG8_BAR; PG8_MMA(0, 0, At, B0); PG8_MMA(0, 1, At, B1); PG8_BAR; PG8_SCHED;
;     ...
;         for (int a = 0; a < 2; ++a)
; #pragma unroll
;             for (int b = 0; b < 2; ++b)
; #pragma unroll
;                 for (int m = 0; m < 4; ++m)
; #pragma unroll
;                     for (int n = 0; n < 2; ++n) acc[a][b][m][n] = (f32x4){0.f, 0.f, 0.f, 0.f};
;         cur = nxt; cA = nA; cB = nB; ++ui;
.LBB0_861:
	v_mov_b32_e32 v2, 0
	s_add_i32 s10, s10, 0x100080
	s_addk_i32 s11, 0x100
	s_mov_b32 s18, -2
	v_mov_b32_e32 v3, v2
	v_mov_b32_e32 v4, v2
	v_mov_b32_e32 v5, v2
	v_mov_b32_e32 v6, v2
	v_mov_b32_e32 v7, v2
	v_mov_b32_e32 v8, v2
	v_mov_b32_e32 v9, v2
	v_mov_b32_e32 v18, v2
	v_mov_b32_e32 v19, v2
	v_mov_b32_e32 v20, v2
	v_mov_b32_e32 v21, v2
	v_mov_b32_e32 v22, v2
	v_mov_b32_e32 v23, v2
	v_mov_b32_e32 v24, v2
	v_mov_b32_e32 v25, v2
	v_mov_b32_e32 v34, v2
	v_mov_b32_e32 v35, v2
	v_mov_b32_e32 v36, v2
	v_mov_b32_e32 v37, v2
	v_mov_b32_e32 v38, v2
	v_mov_b32_e32 v39, v2
	v_mov_b32_e32 v40, v2
	v_mov_b32_e32 v41, v2
	v_mov_b32_e32 v50, v2
	v_mov_b32_e32 v51, v2
	v_mov_b32_e32 v52, v2
	v_mov_b32_e32 v53, v2
	v_mov_b32_e32 v54, v2
	v_mov_b32_e32 v55, v2
	v_mov_b32_e32 v56, v2
	v_mov_b32_e32 v57, v2
	v_mov_b32_e32 v10, v2
	v_mov_b32_e32 v11, v2
	v_mov_b32_e32 v12, v2
	v_mov_b32_e32 v13, v2
	v_mov_b32_e32 v14, v2
	v_mov_b32_e32 v15, v2
	v_mov_b32_e32 v16, v2
	v_mov_b32_e32 v17, v2
	v_mov_b32_e32 v26, v2
	v_mov_b32_e32 v27, v2
	v_mov_b32_e32 v28, v2
	v_mov_b32_e32 v29, v2
	v_mov_b32_e32 v30, v2
	v_mov_b32_e32 v31, v2
	v_mov_b32_e32 v32, v2
	v_mov_b32_e32 v33, v2
	v_mov_b32_e32 v42, v2
	v_mov_b32_e32 v43, v2
	v_mov_b32_e32 v44, v2
	v_mov_b32_e32 v45, v2
	v_mov_b32_e32 v46, v2
	v_mov_b32_e32 v47, v2
	v_mov_b32_e32 v48, v2
	v_mov_b32_e32 v49, v2
	v_mov_b32_e32 v58, v2
	v_mov_b32_e32 v59, v2
	v_mov_b32_e32 v60, v2
	v_mov_b32_e32 v61, v2
	v_mov_b32_e32 v62, v2
	v_mov_b32_e32 v63, v2
	v_mov_b32_e32 v64, v2
	v_mov_b32_e32 v65, v2
	v_mov_b32_e32 v66, v2
	v_mov_b32_e32 v67, v2
	v_mov_b32_e32 v68, v2
	v_mov_b32_e32 v69, v2
	v_mov_b32_e32 v70, v2
	v_mov_b32_e32 v71, v2
	v_mov_b32_e32 v72, v2
	v_mov_b32_e32 v73, v2
	v_mov_b32_e32 v82, v2
	v_mov_b32_e32 v83, v2
	v_mov_b32_e32 v84, v2
	v_mov_b32_e32 v85, v2
	v_mov_b32_e32 v86, v2
	v_mov_b32_e32 v87, v2
	v_mov_b32_e32 v88, v2
	v_mov_b32_e32 v89, v2
	v_mov_b32_e32 v98, v2
	v_mov_b32_e32 v99, v2
	v_mov_b32_e32 v100, v2
	v_mov_b32_e32 v101, v2
	v_mov_b32_e32 v102, v2
	v_mov_b32_e32 v103, v2
	v_mov_b32_e32 v104, v2
	v_mov_b32_e32 v105, v2
	v_mov_b32_e32 v114, v2
	v_mov_b32_e32 v115, v2
	v_mov_b32_e32 v116, v2
	v_mov_b32_e32 v117, v2
	v_mov_b32_e32 v118, v2
	v_mov_b32_e32 v119, v2
	v_mov_b32_e32 v120, v2
	v_mov_b32_e32 v121, v2
	v_mov_b32_e32 v74, v2
	v_mov_b32_e32 v75, v2
	v_mov_b32_e32 v76, v2
	v_mov_b32_e32 v77, v2
	v_mov_b32_e32 v78, v2
	v_mov_b32_e32 v79, v2
	v_mov_b32_e32 v80, v2
	v_mov_b32_e32 v81, v2
	v_mov_b32_e32 v90, v2
	v_mov_b32_e32 v91, v2
	v_mov_b32_e32 v92, v2
	v_mov_b32_e32 v93, v2
	v_mov_b32_e32 v94, v2
	v_mov_b32_e32 v95, v2
	v_mov_b32_e32 v96, v2
	v_mov_b32_e32 v97, v2
	v_mov_b32_e32 v106, v2
	v_mov_b32_e32 v107, v2
	v_mov_b32_e32 v108, v2
	v_mov_b32_e32 v109, v2
	v_mov_b32_e32 v110, v2
	v_mov_b32_e32 v111, v2
	v_mov_b32_e32 v112, v2
	v_mov_b32_e32 v113, v2
	v_mov_b32_e32 v122, v2
	v_mov_b32_e32 v123, v2
	v_mov_b32_e32 v124, v2
	v_mov_b32_e32 v125, v2
	v_mov_b32_e32 v126, v2
	v_mov_b32_e32 v127, v2
	v_mov_b32_e32 v128, v2
	v_mov_b32_e32 v129, v2
	v_readlane_b32 s98, v255, 4
	s_nop 3
	s_cmp_lg_u32 s98, 0
	s_cbranch_scc0 .Lprio_skip_2
	s_setprio 1
.Lprio_skip_2:
.LBB0_862:
	v_readfirstlane_b32 s100, v130
	v_readfirstlane_b32 s101, v131
	s_nop 1
	s_sub_u32 s100, s100, 0x10000000
	s_subb_u32 s101, s101, 0
	s_add_i32 s47, s10, 0xfff00080
	s_cmp_eq_u32 s18, 60
	s_cselect_b32 s83, s45, s47
	s_cselect_b32 s82, s46, s11
	s_add_i32 s84, 0, 0x10000
	s_waitcnt lgkmcnt(0)
	v_add_u32_e32 v0, s84, v144
	s_add_i32 s86, 0, 0x14000
	ds_read_b128 v[136:139], v0
	ds_read_b128 v[146:149], v0 offset:1024
	ds_read_b128 v[150:153], v0 offset:2048
	ds_read_b128 v[154:157], v0 offset:3072
	v_add_u32_e32 v0, s86, v144
	ds_read_b128 v[158:161], v0
	ds_read_b128 v[162:165], v0 offset:1024
	ds_read_b128 v[166:169], v0 offset:2048
	ds_read_b128 v[170:173], v0 offset:3072
	s_add_i32 s47, s83, 0x80
	s_mov_b32 s87, s10
	ds_read_b128 v[174:177], v145
	ds_read_b128 v[178:181], v145 offset:1024
	ds_read_b128 v[182:185], v145 offset:2048
	ds_read_b128 v[186:189], v145 offset:3072
	ds_read_b128 v[190:193], v145 offset:4096
	ds_read_b128 v[194:197], v145 offset:5120
	ds_read_b128 v[198:201], v145 offset:6144
	ds_read_b128 v[202:205], v145 offset:7168
	s_add_i32 m0, s22, 0xc000
	s_add_i32 vcc_lo, s87, 0x10000000
	s_add_u32 vcc_lo, s100, vcc_lo
	s_addc_u32 vcc_hi, s101, 0
	global_load_lds_dwordx4 v140, vcc
	s_add_i32 m0, s22, 0xe000
	s_nop 0
	global_load_lds_dwordx4 v142, vcc
	s_waitcnt vmcnt(8)
	s_waitcnt lgkmcnt(0)
	s_barrier
; #define PG8_STAGE(bufoff, gbase, voff) do { unsigned _g = (gbase); asm volatile("" : "+s"(_g));   _Pragma("unroll") for (int _i = 0; _i < 2; ++_i) \
;         __builtin_amdgcn_global_load_lds((const unsigned*)(wsb + (size_t)(unsigned)(_g + (voff)[_i])), (LAS unsigned*)(lds + (bufoff) + ldsw + _i * 8192), 16, 0, 0); } while (0)
; #define PG8_WAIT_V(n) asm volatile("s_waitcnt vmcnt(" #n ")" ::: "memory")
; #define PG8_WAIT_L(n) asm volatile("s_waitcnt lgkmcnt(" #n ")" ::: "memory")
; #define PG8_BAR __builtin_amdgcn_s_barrier()
; #define PG8_SCHED __builtin_amdgcn_sched_barrier(0)
;     ...
;             PG8_WAIT_V(8); PG8_WAIT_L(0); PG8_BAR; PG8_MMA(0, 0, At, B0); PG8_MMA(0, 1, At, B1); PG8_BAR; PG8_SCHED;
;             PG8_LDA(At, 0, 1); PG8_STAGE(PG8_SB(0, 0), b2, voffB); PG8_STAGE(PG8_SB(0, 1), b2 + hstep, voffB); PG8_STAGE(PG8_SA(0, 0), a2, voffA);
;             PG8_WAIT_V(8); PG8_WAIT_L(0); PG8_BAR; PG8_MMA(1, 0, At, B0); PG8_MMA(1, 1, At, B1); PG8_BAR; PG8_SCHED;
	s_waitcnt lgkmcnt(0)
	v_mfma_f32_16x16x32_bf16 v[126:129], v[136:139], v[174:177], v[126:129]
	v_mfma_f32_16x16x32_bf16 v[122:125], v[150:153], v[174:177], v[122:125]
	v_mfma_f32_16x16x32_bf16 v[110:113], v[136:139], v[182:185], v[110:113]
	v_mfma_f32_16x16x32_bf16 v[106:109], v[150:153], v[182:185], v[106:109]
	v_mfma_f32_16x16x32_bf16 v[94:97], v[136:139], v[190:193], v[94:97]
	v_mfma_f32_16x16x32_bf16 v[90:93], v[150:153], v[190:193], v[90:93]
	v_mfma_f32_16x16x32_bf16 v[78:81], v[136:139], v[198:201], v[78:81]
	v_mfma_f32_16x16x32_bf16 v[74:77], v[150:153], v[198:201], v[74:77]
	v_mfma_f32_16x16x32_bf16 v[126:129], v[146:149], v[178:181], v[126:129]
	v_mfma_f32_16x16x32_bf16 v[122:125], v[154:157], v[178:181], v[122:125]
	v_mfma_f32_16x16x32_bf16 v[110:113], v[146:149], v[186:189], v[110:113]
	v_mfma_f32_16x16x32_bf16 v[106:109], v[154:157], v[186:189], v[106:109]
	v_mfma_f32_16x16x32_bf16 v[94:97], v[146:149], v[194:197], v[94:97]
	v_mfma_f32_16x16x32_bf16 v[90:93], v[154:157], v[194:197], v[90:93]
	v_mfma_f32_16x16x32_bf16 v[78:81], v[146:149], v[202:205], v[78:81]
	v_mfma_f32_16x16x32_bf16 v[74:77], v[154:157], v[202:205], v[74:77]
	v_mfma_f32_16x16x32_bf16 v[118:121], v[158:161], v[174:177], v[118:121]
	v_mfma_f32_16x16x32_bf16 v[114:117], v[166:169], v[174:177], v[114:117]
	v_mfma_f32_16x16x32_bf16 v[102:105], v[158:161], v[182:185], v[102:105]
	v_mfma_f32_16x16x32_bf16 v[98:101], v[166:169], v[182:185], v[98:101]
	v_mfma_f32_16x16x32_bf16 v[86:89], v[158:161], v[190:193], v[86:89]
	v_mfma_f32_16x16x32_bf16 v[82:85], v[166:169], v[190:193], v[82:85]
	v_mfma_f32_16x16x32_bf16 v[70:73], v[158:161], v[198:201], v[70:73]
	v_mfma_f32_16x16x32_bf16 v[66:69], v[166:169], v[198:201], v[66:69]
	v_mfma_f32_16x16x32_bf16 v[118:121], v[162:165], v[178:181], v[118:121]
	v_mfma_f32_16x16x32_bf16 v[114:117], v[170:173], v[178:181], v[114:117]
	v_mfma_f32_16x16x32_bf16 v[102:105], v[162:165], v[186:189], v[102:105]
	v_mfma_f32_16x16x32_bf16 v[98:101], v[170:173], v[186:189], v[98:101]
	v_mfma_f32_16x16x32_bf16 v[86:89], v[162:165], v[194:197], v[86:89]
	v_mfma_f32_16x16x32_bf16 v[82:85], v[170:173], v[194:197], v[82:85]
	v_mfma_f32_16x16x32_bf16 v[70:73], v[162:165], v[202:205], v[70:73]
	v_mfma_f32_16x16x32_bf16 v[66:69], v[170:173], v[202:205], v[66:69]
	s_barrier
	s_mov_b32 s87, s82
	ds_read_b128 v[174:177], v145 offset:16384
	ds_read_b128 v[178:181], v145 offset:17408
	ds_read_b128 v[182:185], v145 offset:18432
	ds_read_b128 v[186:189], v145 offset:19456
	ds_read_b128 v[190:193], v145 offset:20480
	ds_read_b128 v[194:197], v145 offset:21504
	ds_read_b128 v[198:201], v145 offset:22528
	ds_read_b128 v[202:205], v145 offset:23552
	s_add_i32 s84, s84, s7
	s_add_i32 vcc_lo, s87, 0x10000000
	s_add_u32 vcc_lo, s100, vcc_lo
	s_addc_u32 vcc_hi, s101, 0
	s_mov_b32 m0, s84
	s_nop 0
	global_load_lds_dwordx4 v141, vcc
	s_add_i32 m0, s84, 0x2000
	s_add_i32 s84, s82, 0x100000
	global_load_lds_dwordx4 v143, vcc
	s_add_i32 s86, s86, s7
	s_add_i32 vcc_lo, s84, 0x10000000
	s_add_u32 vcc_lo, s100, vcc_lo
	s_addc_u32 vcc_hi, s101, 0
	s_mov_b32 m0, s86
	s_nop 0
	global_load_lds_dwordx4 v141, vcc
	s_add_i32 m0, s86, 0x2000
	s_mov_b32 s84, s83
	global_load_lds_dwordx4 v143, vcc
	s_mov_b32 m0, s22
	s_add_i32 vcc_lo, s84, 0x10000000
	s_add_u32 vcc_lo, s100, vcc_lo
	s_addc_u32 vcc_hi, s101, 0
	global_load_lds_dwordx4 v140, vcc
	s_mov_b32 m0, s23
	s_nop 0
	global_load_lds_dwordx4 v142, vcc
	s_waitcnt vmcnt(8)
	s_waitcnt lgkmcnt(0)
	s_barrier
	s_waitcnt lgkmcnt(0)
	v_mfma_f32_16x16x32_bf16 v[62:65], v[136:139], v[174:177], v[62:65]
	v_mfma_f32_16x16x32_bf16 v[58:61], v[150:153], v[174:177], v[58:61]
	v_mfma_f32_16x16x32_bf16 v[46:49], v[136:139], v[182:185], v[46:49]
	v_mfma_f32_16x16x32_bf16 v[42:45], v[150:153], v[182:185], v[42:45]
	v_mfma_f32_16x16x32_bf16 v[30:33], v[136:139], v[190:193], v[30:33]
	v_mfma_f32_16x16x32_bf16 v[26:29], v[150:153], v[190:193], v[26:29]
	v_mfma_f32_16x16x32_bf16 v[14:17], v[136:139], v[198:201], v[14:17]
	v_mfma_f32_16x16x32_bf16 v[10:13], v[150:153], v[198:201], v[10:13]
	v_mfma_f32_16x16x32_bf16 v[62:65], v[146:149], v[178:181], v[62:65]
	v_mfma_f32_16x16x32_bf16 v[58:61], v[154:157], v[178:181], v[58:61]
	v_mfma_f32_16x16x32_bf16 v[46:49], v[146:149], v[186:189], v[46:49]
	v_mfma_f32_16x16x32_bf16 v[42:45], v[154:157], v[186:189], v[42:45]
	v_mfma_f32_16x16x32_bf16 v[30:33], v[146:149], v[194:197], v[30:33]
	v_mfma_f32_16x16x32_bf16 v[26:29], v[154:157], v[194:197], v[26:29]
	v_mfma_f32_16x16x32_bf16 v[14:17], v[146:149], v[202:205], v[14:17]
	v_mfma_f32_16x16x32_bf16 v[10:13], v[154:157], v[202:205], v[10:13]
	v_mfma_f32_16x16x32_bf16 v[54:57], v[158:161], v[174:177], v[54:57]
	v_mfma_f32_16x16x32_bf16 v[50:53], v[166:169], v[174:177], v[50:53]
	v_mfma_f32_16x16x32_bf16 v[38:41], v[158:161], v[182:185], v[38:41]
	v_mfma_f32_16x16x32_bf16 v[34:37], v[166:169], v[182:185], v[34:37]
	v_mfma_f32_16x16x32_bf16 v[22:25], v[158:161], v[190:193], v[22:25]
	v_mfma_f32_16x16x32_bf16 v[18:21], v[166:169], v[190:193], v[18:21]
	v_mfma_f32_16x16x32_bf16 v[6:9], v[158:161], v[198:201], v[6:9]
	v_mfma_f32_16x16x32_bf16 v[2:5], v[166:169], v[198:201], v[2:5]
	v_mfma_f32_16x16x32_bf16 v[54:57], v[162:165], v[178:181], v[54:57]
	v_mfma_f32_16x16x32_bf16 v[50:53], v[170:173], v[178:181], v[50:53]
	v_mfma_f32_16x16x32_bf16 v[38:41], v[162:165], v[186:189], v[38:41]
	v_mfma_f32_16x16x32_bf16 v[34:37], v[170:173], v[186:189], v[34:37]
	v_mfma_f32_16x16x32_bf16 v[22:25], v[162:165], v[194:197], v[22:25]
	v_mfma_f32_16x16x32_bf16 v[18:21], v[170:173], v[194:197], v[18:21]
	v_mfma_f32_16x16x32_bf16 v[6:9], v[162:165], v[202:205], v[6:9]
	v_mfma_f32_16x16x32_bf16 v[2:5], v[170:173], v[202:205], v[2:5]
	s_barrier
; #define PG8_STAGE(bufoff, gbase, voff) do { unsigned _g = (gbase); asm volatile("" : "+s"(_g));   _Pragma("unroll") for (int _i = 0; _i < 2; ++_i) \
;         __builtin_amdgcn_global_load_lds((const unsigned*)(wsb + (size_t)(unsigned)(_g + (voff)[_i])), (LAS unsigned*)(lds + (bufoff) + ldsw + _i * 8192), 16, 0, 0); } while (0)
; #define PG8_WAIT_V(n) asm volatile("s_waitcnt vmcnt(" #n ")" ::: "memory")
; #define PG8_WAIT_L(n) asm volatile("s_waitcnt lgkmcnt(" #n ")" ::: "memory")
; #define PG8_BAR __builtin_amdgcn_s_barrier()
; #define PG8_SCHED __builtin_amdgcn_sched_barrier(0)
;     ...
;             PG8_LDB(B0, 1, 0); PG8_LDB(B1, 1, 1); PG8_SCHED; PG8_LDA(At, 1, 0); PG8_STAGE(PG8_SA(0, 1), a2 + hstep, voffA);
;             PG8_WAIT_V(8); PG8_WAIT_L(0); PG8_BAR; PG8_MMA(0, 0, At, B0); PG8_MMA(0, 1, At, B1); PG8_BAR; PG8_SCHED;
;             PG8_LDA(At, 1, 1); PG8_STAGE(PG8_SB(1, 0), b3, voffB); PG8_STAGE(PG8_SB(1, 1), b3 + hstep, voffB); PG8_STAGE(PG8_SA(1, 0), a3, voffA);
	s_add_i32 s84, 0, 0x18000
	v_add_u32_e32 v0, s84, v144
	s_add_i32 s86, 0, 0x1c000
	ds_read_b128 v[136:139], v0
	ds_read_b128 v[146:149], v0 offset:1024
	ds_read_b128 v[150:153], v0 offset:2048
	ds_read_b128 v[154:157], v0 offset:3072
	v_add_u32_e32 v0, s86, v144
	ds_read_b128 v[158:161], v0
	ds_read_b128 v[162:165], v0 offset:1024
	ds_read_b128 v[166:169], v0 offset:2048
	ds_read_b128 v[170:173], v0 offset:3072
	s_add_i32 s83, s83, 0x100000
	ds_read_b128 v[174:177], v145 offset:32768
	ds_read_b128 v[178:181], v145 offset:33792
	ds_read_b128 v[182:185], v145 offset:34816
	ds_read_b128 v[186:189], v145 offset:35840
	ds_read_b128 v[190:193], v145 offset:36864
	ds_read_b128 v[194:197], v145 offset:37888
	ds_read_b128 v[198:201], v145 offset:38912
	ds_read_b128 v[202:205], v145 offset:39936
	s_mov_b32 m0, s24
	s_add_i32 vcc_lo, s83, 0x10000000
	s_add_u32 vcc_lo, s100, vcc_lo
	s_addc_u32 vcc_hi, s101, 0
	global_load_lds_dwordx4 v140, vcc
	s_mov_b32 m0, s25
	s_nop 0
	global_load_lds_dwordx4 v142, vcc
	s_waitcnt vmcnt(8)
	s_waitcnt lgkmcnt(0)
	s_barrier
	s_waitcnt lgkmcnt(0)
	v_mfma_f32_16x16x32_bf16 v[126:129], v[136:139], v[174:177], v[126:129]
	v_mfma_f32_16x16x32_bf16 v[122:125], v[150:153], v[174:177], v[122:125]
	v_mfma_f32_16x16x32_bf16 v[110:113], v[136:139], v[182:185], v[110:113]
	v_mfma_f32_16x16x32_bf16 v[106:109], v[150:153], v[182:185], v[106:109]
	v_mfma_f32_16x16x32_bf16 v[94:97], v[136:139], v[190:193], v[94:97]
	v_mfma_f32_16x16x32_bf16 v[90:93], v[150:153], v[190:193], v[90:93]
	v_mfma_f32_16x16x32_bf16 v[78:81], v[136:139], v[198:201], v[78:81]
	v_mfma_f32_16x16x32_bf16 v[74:77], v[150:153], v[198:201], v[74:77]
	v_mfma_f32_16x16x32_bf16 v[126:129], v[146:149], v[178:181], v[126:129]
	v_mfma_f32_16x16x32_bf16 v[122:125], v[154:157], v[178:181], v[122:125]
	v_mfma_f32_16x16x32_bf16 v[110:113], v[146:149], v[186:189], v[110:113]
	v_mfma_f32_16x16x32_bf16 v[106:109], v[154:157], v[186:189], v[106:109]
	v_mfma_f32_16x16x32_bf16 v[94:97], v[146:149], v[194:197], v[94:97]
	v_mfma_f32_16x16x32_bf16 v[90:93], v[154:157], v[194:197], v[90:93]
	v_mfma_f32_16x16x32_bf16 v[78:81], v[146:149], v[202:205], v[78:81]
	v_mfma_f32_16x16x32_bf16 v[74:77], v[154:157], v[202:205], v[74:77]
	v_mfma_f32_16x16x32_bf16 v[118:121], v[158:161], v[174:177], v[118:121]
	v_mfma_f32_16x16x32_bf16 v[114:117], v[166:169], v[174:177], v[114:117]
	v_mfma_f32_16x16x32_bf16 v[102:105], v[158:161], v[182:185], v[102:105]
	v_mfma_f32_16x16x32_bf16 v[98:101], v[166:169], v[182:185], v[98:101]
	v_mfma_f32_16x16x32_bf16 v[86:89], v[158:161], v[190:193], v[86:89]
	v_mfma_f32_16x16x32_bf16 v[82:85], v[166:169], v[190:193], v[82:85]
	v_mfma_f32_16x16x32_bf16 v[70:73], v[158:161], v[198:201], v[70:73]
	v_mfma_f32_16x16x32_bf16 v[66:69], v[166:169], v[198:201], v[66:69]
	v_mfma_f32_16x16x32_bf16 v[118:121], v[162:165], v[178:181], v[118:121]
	v_mfma_f32_16x16x32_bf16 v[114:117], v[170:173], v[178:181], v[114:117]
	v_mfma_f32_16x16x32_bf16 v[102:105], v[162:165], v[186:189], v[102:105]
	v_mfma_f32_16x16x32_bf16 v[98:101], v[170:173], v[186:189], v[98:101]
	v_mfma_f32_16x16x32_bf16 v[86:89], v[162:165], v[194:197], v[86:89]
	v_mfma_f32_16x16x32_bf16 v[82:85], v[170:173], v[194:197], v[82:85]
	v_mfma_f32_16x16x32_bf16 v[70:73], v[162:165], v[202:205], v[70:73]
	v_mfma_f32_16x16x32_bf16 v[66:69], v[170:173], v[202:205], v[66:69]
	s_barrier
	s_add_i32 s83, s82, 0x80
	ds_read_b128 v[174:177], v145 offset:49152
	ds_read_b128 v[178:181], v145 offset:50176
	ds_read_b128 v[182:185], v145 offset:51200
	ds_read_b128 v[186:189], v145 offset:52224
	ds_read_b128 v[190:193], v145 offset:53248
	ds_read_b128 v[194:197], v145 offset:54272
	ds_read_b128 v[198:201], v145 offset:55296
	ds_read_b128 v[202:205], v145 offset:56320
	s_add_i32 s84, s84, s7
	s_add_i32 vcc_lo, s83, 0x10000000
	s_add_u32 vcc_lo, s100, vcc_lo
	s_addc_u32 vcc_hi, s101, 0
	s_mov_b32 m0, s84
	s_nop 0
	global_load_lds_dwordx4 v141, vcc
	s_add_i32 m0, s84, 0x2000
	s_add_i32 s82, s82, 0x100080
	global_load_lds_dwordx4 v143, vcc
	s_add_i32 s83, s86, s7
	s_add_i32 vcc_lo, s82, 0x10000000
	s_add_u32 vcc_lo, s100, vcc_lo
	s_addc_u32 vcc_hi, s101, 0
	s_mov_b32 m0, s83
	s_nop 0
	global_load_lds_dwordx4 v141, vcc
	s_add_i32 m0, s83, 0x2000
	s_nop 0
	global_load_lds_dwordx4 v143, vcc
	s_mov_b32 m0, s36
	s_add_i32 vcc_lo, s47, 0x10000000
	s_add_u32 vcc_lo, s100, vcc_lo
	s_addc_u32 vcc_hi, s101, 0
	global_load_lds_dwordx4 v140, vcc
	s_mov_b32 m0, s37
	s_nop 0
	global_load_lds_dwordx4 v142, vcc
	s_waitcnt vmcnt(8)
	s_waitcnt lgkmcnt(0)
	s_barrier
; #define GAS __attribute__((address_space(1)))
; __device__ __forceinline__ unsigned cvt_pk_bf16(float lo, float hi) { const f32x2_t_ v = {lo, hi}; const bf16x2_t_ b = __builtin_convertvector(v, bf16x2_t_); return __builtin_bit_cast(unsigned, b); }
; #define PG8_WAIT_V(n) asm volatile("s_waitcnt vmcnt(" #n ")" ::: "memory")
; #define PG8_WAIT_L(n) asm volatile("s_waitcnt lgkmcnt(" #n ")" ::: "memory")
; #define PG8_BAR __builtin_amdgcn_s_barrier()
; #define PG8_SCHED __builtin_amdgcn_sched_barrier(0)
;     ...
;             PG8_WAIT_V(8); PG8_WAIT_L(0); PG8_BAR; PG8_MMA(1, 0, At, B0); PG8_MMA(1, 1, At, B1); PG8_BAR; PG8_SCHED;
;     __device__ __forceinline__ void operator()(const f32x4 (&acc)[2][2][4][2], const pg8::GUnit& u, int wr, int wc, int fr, int fq) const {
;         const int row0 = u.pm * 256 + wr * 64 + fr, col0 = u.pn * 256 + wc * 32 + 8 * fq;
; #pragma unroll
;         for (int ai = 0; ai < 2; ++ai)
; #pragma unroll
;             for (int m = 0; m < 4; ++m) { const size_t row = (size_t)(row0 + ai * 128 + m * 16); float s = 0.f;
; #pragma unroll
;                 for (int bj = 0; bj < 2; ++bj) { const f32x4 v0 = acc[ai][bj][m][0], v1 = acc[ai][bj][m][1];
;                     s += (v0[0] * v0[0] + v0[1] * v0[1]) + (v0[2] * v0[2] + v0[3] * v0[3]) + (v1[0] * v1[0] + v1[1] * v1[1]) + (v1[2] * v1[2] + v1[3] * v1[3]);
;                     u32x4 w; w.x = cvt_pk_bf16(v0[0], v0[1]); w.y = cvt_pk_bf16(v0[2], v0[3]); w.z = cvt_pk_bf16(v1[0], v1[1]); w.w = cvt_pk_bf16(v1[2], v1[3]);
;                     *(GAS u32x4*)((GAS bf16_t*)O + row * DM + col0 + bj * 128) = w; }
;                 { const int ln = fr + 16 * fq; s += __int_as_float(__builtin_amdgcn_ds_bpermute((ln ^ 16) << 2, __float_as_int(s))); s += __int_as_float(__builtin_amdgcn_ds_bpermute((ln ^ 32) << 2, __float_as_int(s))); }
;                 if (fq == 0) ((GAS float*)RSQ)[row * 64 + u.pn * 4 + wc] = s; }
	s_waitcnt lgkmcnt(0)
	v_mfma_f32_16x16x32_bf16 v[62:65], v[136:139], v[174:177], v[62:65]
	v_mfma_f32_16x16x32_bf16 v[58:61], v[150:153], v[174:177], v[58:61]
	v_mfma_f32_16x16x32_bf16 v[46:49], v[136:139], v[182:185], v[46:49]
	v_mfma_f32_16x16x32_bf16 v[42:45], v[150:153], v[182:185], v[42:45]
	v_mfma_f32_16x16x32_bf16 v[30:33], v[136:139], v[190:193], v[30:33]
	v_mfma_f32_16x16x32_bf16 v[26:29], v[150:153], v[190:193], v[26:29]
	v_mfma_f32_16x16x32_bf16 v[14:17], v[136:139], v[198:201], v[14:17]
	v_mfma_f32_16x16x32_bf16 v[10:13], v[150:153], v[198:201], v[10:13]
	v_mfma_f32_16x16x32_bf16 v[62:65], v[146:149], v[178:181], v[62:65]
	v_mfma_f32_16x16x32_bf16 v[58:61], v[154:157], v[178:181], v[58:61]
	v_mfma_f32_16x16x32_bf16 v[46:49], v[146:149], v[186:189], v[46:49]
	v_mfma_f32_16x16x32_bf16 v[42:45], v[154:157], v[186:189], v[42:45]
	v_mfma_f32_16x16x32_bf16 v[30:33], v[146:149], v[194:197], v[30:33]
	v_mfma_f32_16x16x32_bf16 v[26:29], v[154:157], v[194:197], v[26:29]
	v_mfma_f32_16x16x32_bf16 v[14:17], v[146:149], v[202:205], v[14:17]
	v_mfma_f32_16x16x32_bf16 v[10:13], v[154:157], v[202:205], v[10:13]
	v_mfma_f32_16x16x32_bf16 v[54:57], v[158:161], v[174:177], v[54:57]
	v_mfma_f32_16x16x32_bf16 v[50:53], v[166:169], v[174:177], v[50:53]
	v_mfma_f32_16x16x32_bf16 v[38:41], v[158:161], v[182:185], v[38:41]
	v_mfma_f32_16x16x32_bf16 v[34:37], v[166:169], v[182:185], v[34:37]
	v_mfma_f32_16x16x32_bf16 v[22:25], v[158:161], v[190:193], v[22:25]
	v_mfma_f32_16x16x32_bf16 v[18:21], v[166:169], v[190:193], v[18:21]
	v_mfma_f32_16x16x32_bf16 v[6:9], v[158:161], v[198:201], v[6:9]
	v_mfma_f32_16x16x32_bf16 v[2:5], v[166:169], v[198:201], v[2:5]
	v_mfma_f32_16x16x32_bf16 v[54:57], v[162:165], v[178:181], v[54:57]
	v_mfma_f32_16x16x32_bf16 v[50:53], v[170:173], v[178:181], v[50:53]
	v_mfma_f32_16x16x32_bf16 v[38:41], v[162:165], v[186:189], v[38:41]
	v_mfma_f32_16x16x32_bf16 v[34:37], v[170:173], v[186:189], v[34:37]
	v_mfma_f32_16x16x32_bf16 v[22:25], v[162:165], v[194:197], v[22:25]
	v_mfma_f32_16x16x32_bf16 v[18:21], v[170:173], v[194:197], v[18:21]
	v_mfma_f32_16x16x32_bf16 v[6:9], v[162:165], v[202:205], v[6:9]
	v_mfma_f32_16x16x32_bf16 v[2:5], v[170:173], v[202:205], v[2:5]
	s_barrier
	s_add_i32 s18, s18, 2
	s_addk_i32 s10, 0x100
	s_addk_i32 s11, 0x100
	s_cmp_gt_u32 s18, 61
	s_cbranch_scc0 .LBB0_862
	s_setprio 0
	s_lshl_b32 s9, s9, 8
	v_mbcnt_lo_u32_b32 v139, -1, 0
	v_mbcnt_hi_u32_b32 v139, -1, v139
	s_add_i32 s9, s9, s3
	v_and_b32_e32 v0, 15, v139
	v_ashrrev_i32_e32 v146, 4, v139
	v_or_b32_e32 v138, s9, v0
	s_lshl_b32 s9, s8, 8
	s_or_b32 s9, s9, s88
	v_lshlrev_b32_e32 v147, 6, v146
	v_lshlrev_b32_e32 v0, 2, v0
	v_lshl_add_u32 v136, v146, 3, s9
	v_bitop3_b32 v146, v147, 64, v0 bitop3:0x36
	v_bitop3_b32 v0, v147, s92, v0 bitop3:0x36
	v_mul_f32_e32 v147, v127, v127
	v_mul_f32_e32 v150, v129, v129
	v_fmac_f32_e32 v147, v126, v126
	v_fmac_f32_e32 v150, v128, v128
	v_add_f32_e32 v147, v147, v150
	v_mul_f32_e32 v150, v123, v123
	v_fmac_f32_e32 v150, v122, v122
	v_cvt_pk_bf16_f32 v126, v126, v127
	v_cvt_pk_bf16_f32 v127, v128, v129
	v_cvt_pk_bf16_f32 v128, v122, v123
	v_mul_f32_e32 v122, v119, v119
	v_mul_f32_e32 v123, v121, v121
	v_fmac_f32_e32 v122, v118, v118
	v_fmac_f32_e32 v123, v120, v120
	v_add_f32_e32 v122, v122, v123
	v_mul_f32_e32 v123, v115, v115
	v_fmac_f32_e32 v123, v114, v114
	v_add_f32_e32 v147, v147, v150
	v_mul_f32_e32 v150, v125, v125
	v_add_f32_e32 v122, v122, v123
	v_mul_f32_e32 v123, v117, v117
	v_fmac_f32_e32 v150, v124, v124
	v_fmac_f32_e32 v123, v116, v116
	v_add_f32_e32 v147, v150, v147
	v_add_f32_e32 v122, v123, v122
	v_cvt_pk_bf16_f32 v129, v124, v125
	v_add_f32_e32 v124, v147, v122
	ds_bpermute_b32 v125, v146, v124
	v_cmp_gt_u32_e32 vcc, 16, v139
	v_ashrrev_i32_e32 v139, 31, v138
	v_lshlrev_b64 v[148:149], 13, v[138:139]
	v_ashrrev_i32_e32 v137, 31, v136
	v_lshl_add_u64 v[122:123], v[132:133], 0, v[148:149]
	v_lshl_add_u64 v[148:149], v[136:137], 1, v[122:123]
	v_cvt_pk_bf16_f32 v122, v118, v119
	s_waitcnt lgkmcnt(0)
	v_add_f32_e32 v118, v124, v125
	ds_bpermute_b32 v119, v0, v118
	s_lshl_b32 s8, s8, 2
	s_ashr_i32 s9, s8, 31
	v_cvt_pk_bf16_f32 v123, v120, v121
	v_cvt_pk_bf16_f32 v124, v114, v115
	v_cvt_pk_bf16_f32 v125, v116, v117
	global_store_dwordx4 v[148:149], v[126:129], off
	global_store_dwordx4 v[148:149], v[122:125], off offset:256
	s_and_saveexec_b64 s[10:11], vcc
	s_cbranch_execz .LBB0_865
	v_lshlrev_b64 v[114:115], 8, v[138:139]
	v_lshl_add_u64 v[114:115], v[134:135], 0, v[114:115]
	v_lshl_add_u64 v[114:115], s[8:9], 2, v[114:115]
	s_lshl_b32 s18, s43, 2
	s_waitcnt lgkmcnt(0)
	v_add_f32_e32 v116, v118, v119
	v_lshl_add_u64 v[114:115], v[114:115], 0, s[18:19]
	global_store_dword v[114:115], v116, off
